# issue the gate/ta loads of both gating epilogues (GEMM2, GEMM3) up front instead of one round at a time
# baseline (speedup 1.0000x reference)
; #define GAS __attribute__((address_space(1)))
; __device__ __forceinline__ void unpack8(const v4u v, float (&f)[8]) { f[0] = bflo(v.x); f[1] = bfhi(v.x); f[2] = bflo(v.y); f[3] = bfhi(v.y); f[4] = bflo(v.z); f[5] = bfhi(v.z); f[6] = bflo(v.w); f[7] = bfhi(v.w); }
; __device__ __forceinline__ v4u pack8(const float (&f)[8]) { v4u o; o.x = cvt_pk_bf16(f[0], f[1]); o.y = cvt_pk_bf16(f[2], f[3]); o.z = cvt_pk_bf16(f[4], f[5]); o.w = cvt_pk_bf16(f[6], f[7]); return o; }
; __device__ __forceinline__ float sigmoidf_(float x) { return __builtin_amdgcn_rcpf(1.f + __expf(-x)); }
;     __device__ __forceinline__ void operator()(const f32x4 (&acc)[2][2][4][2], const pg8::Unit& u, int wr, int wc, int fr, int fq) const {
;         const int row0 = u.pm * 256 + wr * 64 + fr, col0 = u.pn * 256 + wc * 32 + 8 * fq;
; #pragma unroll
;         for (int bj = 0; bj < 2; ++bj) { const int col = col0 + bj * 128;
;             const f32x4 b0 = *(const GAS f32x4*)(bgate + WHICH * DM + col), b1 = *(const GAS f32x4*)(bgate + WHICH * DM + col + 4);
; #pragma unroll
;             for (int aim = 0; aim < 4; ++aim) { const int ai = aim >> 1, mb = (aim & 1) * 2;
;                 v4u gv[4], tv[4];
; #pragma unroll
;                 for (int m = mb; m < mb + 2; ++m) { const int row = row0 + ai * 128 + m * 16;
;                     gv[m] = __builtin_nontemporal_load((const GAS v4u*)(proj + (size_t)row * NPROJ + OFF_GATE + WHICH * DM + col));
;                     if (WHICH == 1) tv[m] = *(const GAS v4u*)(ta + (size_t)row * DM + col); }
; #pragma unroll
;                 for (int m = mb; m < mb + 2; ++m) { const int row = row0 + ai * 128 + m * 16; float g[8]; unpack8(gv[m], g);
;                     const f32x4 a0 = acc[ai][bj][m][0], a1 = acc[ai][bj][m][1]; float r[8];
; #pragma unroll
;                     for (int e = 0; e < 4; ++e) { r[e] = sigmoidf_(g[e] + b0[e]) * a0[e]; r[4 + e] = sigmoidf_(g[4 + e] + b1[e]) * a1[e]; }
;                     if (WHICH == 0) *(GAS v4u*)(ta + (size_t)row * DM + col) = pack8(r);
;                     else { float tf[8]; unpack8(tv[m], tf);
; #pragma unroll
;                         for (int e = 0; e < 8; ++e) r[e] += tf[e];
;                         *(GAS v4u*)(mix + (size_t)row * DM + col) = pack8(r); } }
;             }
;         }
;     }
.LBB0_410:
	v_lshl_add_u32 v164, s22, 8, v170
	v_lshl_or_b32 v154, s9, 8, v179
	v_mov_b64_e32 v[166:167], s[42:43]
	v_ashrrev_i32_e32 v155, 31, v154
	v_readlane_b32 s60, v252, 8
	v_mad_i64_i32 v[140:141], s[0:1], v164, s4, v[166:167]
	s_mov_b64 s[14:15], 0x8000
	v_readlane_b32 s68, v252, 16
	v_readlane_b32 s69, v252, 17
	v_lshl_add_u64 v[160:161], v[140:141], 0, s[14:15]
	v_lshlrev_b64 v[162:163], 1, v[154:155]
	v_lshl_add_u64 v[156:157], v[154:155], 2, s[68:69]
	v_lshl_add_u64 v[140:141], v[160:161], 0, v[162:163]
	global_load_dwordx4 v[100:103], v[156:157], off offset:16
	global_load_dwordx4 v[104:107], v[156:157], off
	global_load_dwordx4 v[186:189], v[140:141], off nt
	v_or_b32_e32 v168, 16, v164
	v_mad_i64_i32 v[140:141], s[0:1], v168, s4, v[166:167]
	v_lshl_add_u64 v[158:159], v[140:141], 0, s[14:15]
	v_lshl_add_u64 v[140:141], v[158:159], 0, v[162:163]
	global_load_dwordx4 v[140:143], v[140:141], off nt
	s_nop 1
	v_or_b32_e32 v251, 32, v164
	v_mad_i64_i32 v[248:249], s[16:17], v251, s4, v[166:167]
	v_lshl_add_u64 v[246:247], v[248:249], 0, s[14:15]
	v_lshl_add_u64 v[244:245], v[246:247], 0, v[162:163]
	global_load_dwordx4 v[234:237], v[244:245], off nt
	v_or_b32_e32 v251, 48, v164
	v_mad_i64_i32 v[248:249], s[16:17], v251, s4, v[166:167]
	v_lshl_add_u64 v[246:247], v[248:249], 0, s[14:15]
	v_lshl_add_u64 v[244:245], v[246:247], 0, v[162:163]
	global_load_dwordx4 v[230:233], v[244:245], off nt
	v_add_u32_e32 v251, 0x80, v164
	v_mad_i64_i32 v[248:249], s[16:17], v251, s4, v[166:167]
	v_lshl_add_u64 v[246:247], v[248:249], 0, s[14:15]
	v_lshl_add_u64 v[244:245], v[246:247], 0, v[162:163]
	global_load_dwordx4 v[226:229], v[244:245], off nt
	v_add_u32_e32 v251, 0x90, v164
	v_mad_i64_i32 v[248:249], s[16:17], v251, s4, v[166:167]
	v_lshl_add_u64 v[246:247], v[248:249], 0, s[14:15]
	v_lshl_add_u64 v[244:245], v[246:247], 0, v[162:163]
	global_load_dwordx4 v[222:225], v[244:245], off nt
	v_add_u32_e32 v251, 0xa0, v164
	v_mad_i64_i32 v[248:249], s[16:17], v251, s4, v[166:167]
	v_lshl_add_u64 v[246:247], v[248:249], 0, s[14:15]
	v_lshl_add_u64 v[244:245], v[246:247], 0, v[162:163]
	global_load_dwordx4 v[218:221], v[244:245], off nt
	v_add_u32_e32 v251, 0xb0, v164
	v_mad_i64_i32 v[248:249], s[16:17], v251, s4, v[166:167]
	v_lshl_add_u64 v[246:247], v[248:249], 0, s[14:15]
	v_lshl_add_u64 v[244:245], v[246:247], 0, v[162:163]
	global_load_dwordx4 v[214:217], v[244:245], off nt
	global_load_dwordx4 v[248:251], v[156:157], off offset:528
	global_load_dwordx4 v[244:247], v[156:157], off offset:512
	v_or_b32_e32 v243, 0x80, v154
	v_ashrrev_i32_e32 v213, 31, v243
	v_mov_b32_e32 v208, v243
	v_mov_b32_e32 v209, v213
	v_lshlrev_b64 v[210:211], 1, v[208:209]
	v_lshl_add_u64 v[206:207], v[160:161], 0, v[210:211]
	global_load_dwordx4 v[202:205], v[206:207], off nt
	v_or_b32_e32 v243, 0x80, v154
	v_ashrrev_i32_e32 v213, 31, v243
	v_mov_b32_e32 v208, v243
	v_mov_b32_e32 v209, v213
	v_lshlrev_b64 v[210:211], 1, v[208:209]
	v_lshl_add_u64 v[206:207], v[158:159], 0, v[210:211]
	global_load_dwordx4 v[198:201], v[206:207], off nt
	v_ashrrev_i32_e32 v165, 31, v164
	v_ashrrev_i32_e32 v169, 31, v168
	s_andn2_b64 vcc, exec, s[40:41]
	v_readlane_b32 s61, v252, 9
	v_readlane_b32 s62, v252, 10
	v_readlane_b32 s63, v252, 11
	v_readlane_b32 s64, v252, 12
	v_readlane_b32 s65, v252, 13
	v_readlane_b32 s66, v252, 14
	v_readlane_b32 s67, v252, 15
	v_readlane_b32 s70, v252, 18
	v_readlane_b32 s71, v252, 19
	v_readlane_b32 s72, v252, 20
	v_readlane_b32 s73, v252, 21
	v_readlane_b32 s74, v252, 22
	v_readlane_b32 s75, v252, 23
	s_waitcnt vmcnt(10)
	v_lshlrev_b32_e32 v155, 16, v186
	v_add_f32_e32 v155, v104, v155
	v_mul_f32_e32 v155, 0xbfb8aa3b, v155
	v_exp_f32_e32 v155, v155
	v_lshlrev_b32_e32 v190, 16, v188
	v_and_b32_e32 v185, 0xffff0000, v186
	v_and_b32_e32 v188, 0xffff0000, v188
	v_add_f32_e32 v155, 1.0, v155
	v_rcp_f32_e32 v155, v155
	v_lshlrev_b32_e32 v186, 16, v187
	v_lshlrev_b32_e32 v191, 16, v189
	v_and_b32_e32 v187, 0xffff0000, v187
	v_mul_f32_e32 v136, v136, v155
	v_add_f32_e32 v155, v100, v190
	v_mul_f32_e32 v155, 0xbfb8aa3b, v155
	v_exp_f32_e32 v155, v155
	v_and_b32_e32 v189, 0xffff0000, v189
	v_add_f32_e32 v155, 1.0, v155
	v_rcp_f32_e32 v155, v155
	s_nop 0
	v_mul_f32_e32 v155, v132, v155
	v_add_f32_e32 v132, v105, v185
	v_mul_f32_e32 v132, 0xbfb8aa3b, v132
	v_exp_f32_e32 v132, v132
	s_nop 0
	v_add_f32_e32 v132, 1.0, v132
	v_rcp_f32_e32 v132, v132
	s_nop 0
	v_mul_f32_e32 v132, v137, v132
	v_add_f32_e32 v137, v101, v188
	v_mul_f32_e32 v137, 0xbfb8aa3b, v137
	v_exp_f32_e32 v137, v137
	v_cvt_pk_bf16_f32 v132, v136, v132
	s_nop 0
	v_add_f32_e32 v137, 1.0, v137
	v_rcp_f32_e32 v137, v137
	s_nop 0
	v_mul_f32_e32 v137, v133, v137
	v_add_f32_e32 v133, v106, v186
	v_mul_f32_e32 v133, 0xbfb8aa3b, v133
	v_exp_f32_e32 v133, v133
	s_nop 0
	v_add_f32_e32 v133, 1.0, v133
	v_rcp_f32_e32 v133, v133
	s_nop 0
	v_mul_f32_e32 v133, v138, v133
	v_add_f32_e32 v138, v102, v191
	v_mul_f32_e32 v138, 0xbfb8aa3b, v138
	v_exp_f32_e32 v138, v138
	s_nop 0
	v_add_f32_e32 v138, 1.0, v138
	v_rcp_f32_e32 v138, v138
	s_nop 0
	v_mul_f32_e32 v138, v134, v138
	v_add_f32_e32 v134, v107, v187
	v_mul_f32_e32 v134, 0xbfb8aa3b, v134
	v_exp_f32_e32 v134, v134
	s_nop 0
	v_add_f32_e32 v134, 1.0, v134
	v_rcp_f32_e32 v134, v134
	s_nop 0
	v_mul_f32_e32 v134, v139, v134
	v_add_f32_e32 v139, v103, v189
	v_mul_f32_e32 v139, 0xbfb8aa3b, v139
	v_exp_f32_e32 v139, v139
	v_cvt_pk_bf16_f32 v133, v133, v134
	v_cvt_pk_bf16_f32 v134, v155, v137
	v_lshlrev_b64 v[136:137], 12, v[164:165]
	v_add_f32_e32 v139, 1.0, v139
	v_rcp_f32_e32 v139, v139
	v_lshl_add_u64 v[136:137], s[44:45], 0, v[136:137]
	v_lshl_add_u64 v[136:137], v[136:137], 0, v[162:163]
; #define GAS __attribute__((address_space(1)))
; __device__ __forceinline__ void unpack8(const v4u v, float (&f)[8]) { f[0] = bflo(v.x); f[1] = bfhi(v.x); f[2] = bflo(v.y); f[3] = bfhi(v.y); f[4] = bflo(v.z); f[5] = bfhi(v.z); f[6] = bflo(v.w); f[7] = bfhi(v.w); }
; __device__ __forceinline__ v4u pack8(const float (&f)[8]) { v4u o; o.x = cvt_pk_bf16(f[0], f[1]); o.y = cvt_pk_bf16(f[2], f[3]); o.z = cvt_pk_bf16(f[4], f[5]); o.w = cvt_pk_bf16(f[6], f[7]); return o; }
; __device__ __forceinline__ float sigmoidf_(float x) { return __builtin_amdgcn_rcpf(1.f + __expf(-x)); }
;     __device__ __forceinline__ void operator()(const f32x4 (&acc)[2][2][4][2], const pg8::Unit& u, int wr, int wc, int fr, int fq) const {
;     ...
;         for (int bj = 0; bj < 2; ++bj) { const int col = col0 + bj * 128;
;             const f32x4 b0 = *(const GAS f32x4*)(bgate + WHICH * DM + col), b1 = *(const GAS f32x4*)(bgate + WHICH * DM + col + 4);
; #pragma unroll
;             for (int aim = 0; aim < 4; ++aim) { const int ai = aim >> 1, mb = (aim & 1) * 2;
;                 v4u gv[4], tv[4];
; #pragma unroll
;                 for (int m = mb; m < mb + 2; ++m) { const int row = row0 + ai * 128 + m * 16;
;                     gv[m] = __builtin_nontemporal_load((const GAS v4u*)(proj + (size_t)row * NPROJ + OFF_GATE + WHICH * DM + col));
;                     if (WHICH == 1) tv[m] = *(const GAS v4u*)(ta + (size_t)row * DM + col); }
; #pragma unroll
;                 for (int m = mb; m < mb + 2; ++m) { const int row = row0 + ai * 128 + m * 16; float g[8]; unpack8(gv[m], g);
;                     const f32x4 a0 = acc[ai][bj][m][0], a1 = acc[ai][bj][m][1]; float r[8];
; #pragma unroll
;                     for (int e = 0; e < 4; ++e) { r[e] = sigmoidf_(g[e] + b0[e]) * a0[e]; r[4 + e] = sigmoidf_(g[4 + e] + b1[e]) * a1[e]; }
;                     if (WHICH == 0) *(GAS v4u*)(ta + (size_t)row * DM + col) = pack8(r);
;                     else { float tf[8]; unpack8(tv[m], tf);
; #pragma unroll
;                         for (int e = 0; e < 8; ++e) r[e] += tf[e];
;                         *(GAS v4u*)(mix + (size_t)row * DM + col) = pack8(r); } }
	v_mul_f32_e32 v135, v135, v139
	v_cvt_pk_bf16_f32 v135, v138, v135
	global_store_dwordx4 v[136:137], v[132:135], off
	v_or_b32_e32 v243, 48, v164
	v_mad_i64_i32 v[212:213], s[16:17], v243, s4, v[166:167]
	v_lshl_add_u64 v[210:211], v[212:213], 0, s[14:15]
	v_or_b32_e32 v209, 0x80, v154
	v_ashrrev_i32_e32 v208, 31, v209
	v_mov_b32_e32 v196, v209
	v_mov_b32_e32 v197, v208
	v_lshlrev_b64 v[206:207], 1, v[196:197]
	v_lshl_add_u64 v[194:195], v[210:211], 0, v[206:207]
	global_load_dwordx4 v[190:193], v[194:195], off nt
	v_or_b32_e32 v243, 32, v164
	v_mad_i64_i32 v[212:213], s[16:17], v243, s4, v[166:167]
	v_lshl_add_u64 v[210:211], v[212:213], 0, s[14:15]
	v_or_b32_e32 v209, 0x80, v154
	v_ashrrev_i32_e32 v208, 31, v209
	v_mov_b32_e32 v196, v209
	v_mov_b32_e32 v197, v208
	v_lshlrev_b64 v[206:207], 1, v[196:197]
	v_lshl_add_u64 v[194:195], v[210:211], 0, v[206:207]
	global_load_dwordx4 v[186:189], v[194:195], off nt
	v_lshlrev_b32_e32 v138, 16, v142
	v_and_b32_e32 v139, 0xffff0000, v142
	v_lshlrev_b32_e32 v132, 16, v140
	v_add_f32_e32 v132, v104, v132
	v_mul_f32_e32 v132, 0xbfb8aa3b, v132
	v_exp_f32_e32 v132, v132
	v_and_b32_e32 v133, 0xffff0000, v140
	v_lshlrev_b32_e32 v134, 16, v141
	v_lshlrev_b32_e32 v140, 16, v143
	v_add_f32_e32 v132, 1.0, v132
	v_rcp_f32_e32 v132, v132
	v_and_b32_e32 v135, 0xffff0000, v141
	v_and_b32_e32 v141, 0xffff0000, v143
	v_mul_f32_e32 v128, v128, v132
	v_add_f32_e32 v132, v100, v138
	v_mul_f32_e32 v132, 0xbfb8aa3b, v132
	v_exp_f32_e32 v132, v132
	v_or_b32_e32 v138, 32, v164
	v_add_f32_e32 v132, 1.0, v132
	v_rcp_f32_e32 v132, v132
	s_nop 0
	v_mul_f32_e32 v132, v124, v132
	v_add_f32_e32 v124, v105, v133
	v_mul_f32_e32 v124, 0xbfb8aa3b, v124
	v_exp_f32_e32 v124, v124
	s_nop 0
	v_add_f32_e32 v124, 1.0, v124
	v_rcp_f32_e32 v124, v124
	s_nop 0
	v_mul_f32_e32 v124, v129, v124
	v_add_f32_e32 v129, v101, v139
	v_mul_f32_e32 v129, 0xbfb8aa3b, v129
	v_exp_f32_e32 v129, v129
	v_cvt_pk_bf16_f32 v124, v128, v124
	v_ashrrev_i32_e32 v139, 31, v138
	v_add_f32_e32 v129, 1.0, v129
	v_rcp_f32_e32 v129, v129
	s_nop 0
	v_mul_f32_e32 v129, v125, v129
	v_add_f32_e32 v125, v106, v134
	v_mul_f32_e32 v125, 0xbfb8aa3b, v125
	v_exp_f32_e32 v125, v125
	v_or_b32_e32 v134, 48, v164
	v_add_f32_e32 v125, 1.0, v125
	v_rcp_f32_e32 v125, v125
	s_nop 0
	v_mul_f32_e32 v125, v130, v125
	v_add_f32_e32 v130, v102, v140
	v_mul_f32_e32 v130, 0xbfb8aa3b, v130
	v_exp_f32_e32 v130, v130
	s_nop 0
	v_add_f32_e32 v130, 1.0, v130
	v_rcp_f32_e32 v130, v130
	s_nop 0
	v_mul_f32_e32 v130, v126, v130
	v_add_f32_e32 v126, v107, v135
	v_mul_f32_e32 v126, 0xbfb8aa3b, v126
	v_exp_f32_e32 v126, v126
	v_ashrrev_i32_e32 v135, 31, v134
	v_add_f32_e32 v126, 1.0, v126
	v_rcp_f32_e32 v126, v126
	s_nop 0
	v_mul_f32_e32 v126, v131, v126
	v_add_f32_e32 v131, v103, v141
	v_mul_f32_e32 v131, 0xbfb8aa3b, v131
	v_exp_f32_e32 v131, v131
	v_cvt_pk_bf16_f32 v125, v125, v126
	v_cvt_pk_bf16_f32 v126, v132, v129
	v_lshlrev_b64 v[128:129], 12, v[168:169]
	v_add_f32_e32 v131, 1.0, v131
	v_rcp_f32_e32 v131, v131
	v_lshl_add_u64 v[128:129], s[44:45], 0, v[128:129]
	v_lshl_add_u64 v[128:129], v[128:129], 0, v[162:163]
	v_mul_f32_e32 v127, v127, v131
	v_cvt_pk_bf16_f32 v127, v130, v127
	global_store_dwordx4 v[128:129], v[124:127], off
	s_nop 1
	v_mad_i64_i32 v[124:125], s[0:1], v138, s4, v[166:167]
	v_lshl_add_u64 v[130:131], v[124:125], 0, s[14:15]
	v_lshl_add_u64 v[124:125], v[130:131], 0, v[162:163]
	s_nop 0
	v_mad_i64_i32 v[124:125], s[0:1], v134, s4, v[166:167]
	v_lshl_add_u64 v[132:133], v[124:125], 0, s[14:15]
	v_lshl_add_u64 v[124:125], v[132:133], 0, v[162:163]
	s_nop 0
	s_waitcnt vmcnt(13)
	v_lshlrev_b32_e32 v155, 16, v234
	v_and_b32_e32 v140, 0xffff0000, v234
	v_add_f32_e32 v140, v105, v140
	v_mul_f32_e32 v140, 0xbfb8aa3b, v140
	v_exp_f32_e32 v140, v140
	v_lshlrev_b32_e32 v168, 16, v236
	v_and_b32_e32 v142, 0xffff0000, v236
	v_lshlrev_b32_e32 v165, 16, v235
	v_add_f32_e32 v140, 1.0, v140
	v_rcp_f32_e32 v140, v140
	v_lshlrev_b32_e32 v169, 16, v237
	v_and_b32_e32 v141, 0xffff0000, v235
	v_add_f32_e32 v155, v104, v155
	v_mul_f32_e32 v121, v121, v140
	v_add_f32_e32 v140, v101, v142
	v_mul_f32_e32 v140, 0xbfb8aa3b, v140
	v_exp_f32_e32 v140, v140
	v_mul_f32_e32 v155, 0xbfb8aa3b, v155
	v_exp_f32_e32 v155, v155
	v_and_b32_e32 v143, 0xffff0000, v237
	v_add_f32_e32 v140, 1.0, v140
	v_rcp_f32_e32 v140, v140
	v_add_f32_e32 v155, 1.0, v155
	v_rcp_f32_e32 v155, v155
	v_mul_f32_e32 v117, v117, v140
	v_add_f32_e32 v140, v106, v165
	v_mul_f32_e32 v140, 0xbfb8aa3b, v140
	v_exp_f32_e32 v140, v140
	v_mul_f32_e32 v120, v120, v155
	v_add_f32_e32 v155, v100, v168
	v_mul_f32_e32 v155, 0xbfb8aa3b, v155
	v_add_f32_e32 v140, 1.0, v140
	v_rcp_f32_e32 v140, v140
	v_exp_f32_e32 v155, v155
	v_mul_f32_e32 v122, v122, v140
	v_add_f32_e32 v140, v102, v169
	v_mul_f32_e32 v140, 0xbfb8aa3b, v140
	v_exp_f32_e32 v140, v140
	v_add_f32_e32 v155, 1.0, v155
	v_rcp_f32_e32 v155, v155
	v_add_f32_e32 v140, 1.0, v140
	v_rcp_f32_e32 v140, v140
	v_mul_f32_e32 v116, v116, v155
	v_mul_f32_e32 v140, v118, v140
	v_add_f32_e32 v118, v107, v141
	v_mul_f32_e32 v118, 0xbfb8aa3b, v118
	v_exp_f32_e32 v118, v118
	s_nop 0
	v_add_f32_e32 v118, 1.0, v118
	v_rcp_f32_e32 v118, v118
	s_nop 0
	v_mul_f32_e32 v123, v123, v118
	v_add_f32_e32 v118, v103, v143
	v_mul_f32_e32 v118, 0xbfb8aa3b, v118
	v_exp_f32_e32 v118, v118
	s_nop 0
	v_add_f32_e32 v118, 1.0, v118
	v_rcp_f32_e32 v118, v118
	s_nop 0
	v_mul_f32_e32 v141, v119, v118
	v_cvt_pk_bf16_f32 v118, v120, v121
	v_cvt_pk_bf16_f32 v119, v122, v123
	v_cvt_pk_bf16_f32 v120, v116, v117
	v_lshlrev_b64 v[116:117], 12, v[138:139]
	v_lshl_add_u64 v[116:117], s[44:45], 0, v[116:117]
	v_lshl_add_u64 v[116:117], v[116:117], 0, v[162:163]
	v_cvt_pk_bf16_f32 v121, v140, v141
	global_store_dwordx4 v[116:117], v[118:121], off
	v_or_b32_e32 v243, 0x80, v154
	v_ashrrev_i32_e32 v237, 31, v243
	v_mov_b32_e32 v212, v243
	v_mov_b32_e32 v213, v237
	v_lshlrev_b64 v[234:235], 1, v[212:213]
	v_add_u32_e32 v236, 0x90, v164
	v_mad_i64_i32 v[210:211], s[16:17], v236, s4, v[166:167]
	v_lshl_add_u64 v[208:209], v[210:211], 0, s[14:15]
	v_lshl_add_u64 v[206:207], v[208:209], 0, v[234:235]
	global_load_dwordx4 v[194:197], v[206:207], off nt
	v_or_b32_e32 v243, 0x80, v154
	v_ashrrev_i32_e32 v237, 31, v243
	v_mov_b32_e32 v212, v243
	v_mov_b32_e32 v213, v237
	v_lshlrev_b64 v[234:235], 1, v[212:213]
	v_add_u32_e32 v236, 0x80, v164
	v_mad_i64_i32 v[210:211], s[16:17], v236, s4, v[166:167]
	v_lshl_add_u64 v[208:209], v[210:211], 0, s[14:15]
	v_lshl_add_u64 v[206:207], v[208:209], 0, v[234:235]
	global_load_dwordx4 v[140:143], v[206:207], off nt
	s_waitcnt vmcnt(15)
; #define GAS __attribute__((address_space(1)))
; __device__ __forceinline__ void unpack8(const v4u v, float (&f)[8]) { f[0] = bflo(v.x); f[1] = bfhi(v.x); f[2] = bflo(v.y); f[3] = bfhi(v.y); f[4] = bflo(v.z); f[5] = bfhi(v.z); f[6] = bflo(v.w); f[7] = bfhi(v.w); }
; __device__ __forceinline__ v4u pack8(const float (&f)[8]) { v4u o; o.x = cvt_pk_bf16(f[0], f[1]); o.y = cvt_pk_bf16(f[2], f[3]); o.z = cvt_pk_bf16(f[4], f[5]); o.w = cvt_pk_bf16(f[6], f[7]); return o; }
; __device__ __forceinline__ float sigmoidf_(float x) { return __builtin_amdgcn_rcpf(1.f + __expf(-x)); }
;     __device__ __forceinline__ void operator()(const f32x4 (&acc)[2][2][4][2], const pg8::Unit& u, int wr, int wc, int fr, int fq) const {
;     ...
;         for (int bj = 0; bj < 2; ++bj) { const int col = col0 + bj * 128;
;             const f32x4 b0 = *(const GAS f32x4*)(bgate + WHICH * DM + col), b1 = *(const GAS f32x4*)(bgate + WHICH * DM + col + 4);
; #pragma unroll
;             for (int aim = 0; aim < 4; ++aim) { const int ai = aim >> 1, mb = (aim & 1) * 2;
;                 v4u gv[4], tv[4];
; #pragma unroll
;                 for (int m = mb; m < mb + 2; ++m) { const int row = row0 + ai * 128 + m * 16;
;                     gv[m] = __builtin_nontemporal_load((const GAS v4u*)(proj + (size_t)row * NPROJ + OFF_GATE + WHICH * DM + col));
;                     if (WHICH == 1) tv[m] = *(const GAS v4u*)(ta + (size_t)row * DM + col); }
; #pragma unroll
;                 for (int m = mb; m < mb + 2; ++m) { const int row = row0 + ai * 128 + m * 16; float g[8]; unpack8(gv[m], g);
;                     const f32x4 a0 = acc[ai][bj][m][0], a1 = acc[ai][bj][m][1]; float r[8];
; #pragma unroll
;                     for (int e = 0; e < 4; ++e) { r[e] = sigmoidf_(g[e] + b0[e]) * a0[e]; r[4 + e] = sigmoidf_(g[4 + e] + b1[e]) * a1[e]; }
;                     if (WHICH == 0) *(GAS v4u*)(ta + (size_t)row * DM + col) = pack8(r);
;                     else { float tf[8]; unpack8(tv[m], tf);
; #pragma unroll
;                         for (int e = 0; e < 8; ++e) r[e] += tf[e];
;                         *(GAS v4u*)(mix + (size_t)row * DM + col) = pack8(r); } }
	v_lshlrev_b32_e32 v122, 16, v232
	v_and_b32_e32 v123, 0xffff0000, v232
	v_lshlrev_b32_e32 v118, 16, v230
	v_add_f32_e32 v118, v104, v118
	v_mul_f32_e32 v118, 0xbfb8aa3b, v118
	v_exp_f32_e32 v118, v118
	v_and_b32_e32 v119, 0xffff0000, v230
	v_lshlrev_b32_e32 v120, 16, v231
	v_lshlrev_b32_e32 v124, 16, v233
	v_add_f32_e32 v118, 1.0, v118
	v_rcp_f32_e32 v118, v118
	v_and_b32_e32 v121, 0xffff0000, v231
	v_and_b32_e32 v125, 0xffff0000, v233
	v_add_u32_e32 v126, 0x80, v164
	v_mul_f32_e32 v112, v112, v118
	v_add_f32_e32 v118, v100, v122
	v_mul_f32_e32 v118, 0xbfb8aa3b, v118
	v_exp_f32_e32 v118, v118
	v_ashrrev_i32_e32 v127, 31, v126
	v_add_f32_e32 v118, 1.0, v118
	v_rcp_f32_e32 v118, v118
	s_nop 0
	v_mul_f32_e32 v108, v108, v118
	v_add_f32_e32 v118, v105, v119
	v_mul_f32_e32 v118, 0xbfb8aa3b, v118
	v_exp_f32_e32 v118, v118
	s_nop 0
	v_add_f32_e32 v118, 1.0, v118
	v_rcp_f32_e32 v118, v118
	s_nop 0
	v_mul_f32_e32 v113, v113, v118
	v_add_f32_e32 v118, v101, v123
	v_mul_f32_e32 v118, 0xbfb8aa3b, v118
	v_exp_f32_e32 v118, v118
	s_nop 0
	v_add_f32_e32 v118, 1.0, v118
	v_rcp_f32_e32 v118, v118
	s_nop 0
	v_mul_f32_e32 v109, v109, v118
	v_add_f32_e32 v118, v106, v120
	v_mul_f32_e32 v118, 0xbfb8aa3b, v118
	v_exp_f32_e32 v118, v118
	s_nop 0
	v_add_f32_e32 v118, 1.0, v118
	v_rcp_f32_e32 v118, v118
	s_nop 0
	v_mul_f32_e32 v114, v114, v118
	v_add_f32_e32 v118, v102, v124
	v_mul_f32_e32 v118, 0xbfb8aa3b, v118
	v_exp_f32_e32 v118, v118
	s_nop 0
	v_add_f32_e32 v118, 1.0, v118
	v_rcp_f32_e32 v118, v118
	s_nop 0
	v_mul_f32_e32 v118, v110, v118
	v_add_f32_e32 v110, v107, v121
	v_mul_f32_e32 v110, 0xbfb8aa3b, v110
	v_exp_f32_e32 v110, v110
	s_nop 0
	v_add_f32_e32 v110, 1.0, v110
	v_rcp_f32_e32 v110, v110
	s_nop 0
	v_mul_f32_e32 v115, v115, v110
	v_add_f32_e32 v110, v103, v125
	v_mul_f32_e32 v110, 0xbfb8aa3b, v110
	v_exp_f32_e32 v110, v110
	s_nop 0
	v_add_f32_e32 v110, 1.0, v110
	v_rcp_f32_e32 v110, v110
	s_nop 0
	v_mul_f32_e32 v119, v111, v110
	v_cvt_pk_bf16_f32 v110, v112, v113
	v_cvt_pk_bf16_f32 v111, v114, v115
	v_cvt_pk_bf16_f32 v112, v108, v109
	v_lshlrev_b64 v[108:109], 12, v[134:135]
	v_lshl_add_u64 v[108:109], s[44:45], 0, v[108:109]
	v_lshl_add_u64 v[108:109], v[108:109], 0, v[162:163]
	v_cvt_pk_bf16_f32 v113, v118, v119
	global_store_dwordx4 v[108:109], v[110:113], off
	v_or_b32_e32 v243, 0x80, v154
	v_ashrrev_i32_e32 v237, 31, v243
	v_mov_b32_e32 v232, v243
	v_mov_b32_e32 v233, v237
	v_lshlrev_b64 v[234:235], 1, v[232:233]
	v_add_u32_e32 v236, 0xb0, v164
	v_mad_i64_i32 v[230:231], s[16:17], v236, s4, v[166:167]
	v_lshl_add_u64 v[212:213], v[230:231], 0, s[14:15]
	v_lshl_add_u64 v[210:211], v[212:213], 0, v[234:235]
	global_load_dwordx4 v[206:209], v[210:211], off nt
	v_add_u32_e32 v114, 0x90, v164
	v_ashrrev_i32_e32 v115, 31, v114
	v_mad_i64_i32 v[110:111], s[0:1], v126, s4, v[166:167]
	v_lshl_add_u64 v[110:111], v[110:111], 0, s[14:15]
	v_lshl_add_u64 v[112:113], v[110:111], 0, v[162:163]
	s_nop 0
	v_mad_i64_i32 v[112:113], s[0:1], v114, s4, v[166:167]
	v_lshl_add_u64 v[112:113], v[112:113], 0, s[14:15]
	v_lshl_add_u64 v[122:123], v[112:113], 0, v[162:163]
	s_nop 0
	s_waitcnt vmcnt(16)
	v_lshlrev_b32_e32 v134, 16, v226
	v_and_b32_e32 v118, 0xffff0000, v226
	v_add_f32_e32 v118, v105, v118
	v_mul_f32_e32 v118, 0xbfb8aa3b, v118
	v_exp_f32_e32 v118, v118
	v_lshlrev_b32_e32 v138, 16, v228
	v_and_b32_e32 v120, 0xffff0000, v228
	v_lshlrev_b32_e32 v135, 16, v227
	v_add_f32_e32 v118, 1.0, v118
	v_rcp_f32_e32 v118, v118
	v_lshlrev_b32_e32 v139, 16, v229
	v_and_b32_e32 v119, 0xffff0000, v227
	v_add_f32_e32 v134, v104, v134
	v_mul_f32_e32 v97, v97, v118
	v_add_f32_e32 v118, v101, v120
	v_mul_f32_e32 v118, 0xbfb8aa3b, v118
	v_exp_f32_e32 v118, v118
	v_mul_f32_e32 v134, 0xbfb8aa3b, v134
	v_exp_f32_e32 v134, v134
	v_and_b32_e32 v121, 0xffff0000, v229
	v_add_f32_e32 v118, 1.0, v118
	v_rcp_f32_e32 v118, v118
	v_add_f32_e32 v134, 1.0, v134
	v_rcp_f32_e32 v134, v134
	v_mul_f32_e32 v93, v93, v118
	v_add_f32_e32 v118, v106, v135
	v_mul_f32_e32 v118, 0xbfb8aa3b, v118
	v_exp_f32_e32 v118, v118
	v_mul_f32_e32 v96, v96, v134
	v_add_f32_e32 v134, v100, v138
	v_mul_f32_e32 v134, 0xbfb8aa3b, v134
	v_add_f32_e32 v118, 1.0, v118
	v_rcp_f32_e32 v118, v118
	v_exp_f32_e32 v134, v134
	v_mul_f32_e32 v98, v98, v118
	v_add_f32_e32 v118, v102, v139
	v_mul_f32_e32 v118, 0xbfb8aa3b, v118
	v_exp_f32_e32 v118, v118
	v_add_f32_e32 v134, 1.0, v134
	v_rcp_f32_e32 v134, v134
	v_add_f32_e32 v118, 1.0, v118
	v_rcp_f32_e32 v118, v118
	v_mul_f32_e32 v92, v92, v134
	v_mul_f32_e32 v118, v94, v118
	v_add_f32_e32 v94, v107, v119
	v_mul_f32_e32 v94, 0xbfb8aa3b, v94
	v_exp_f32_e32 v94, v94
	s_nop 0
	v_add_f32_e32 v94, 1.0, v94
	v_rcp_f32_e32 v94, v94
	s_nop 0
	v_mul_f32_e32 v99, v99, v94
	v_add_f32_e32 v94, v103, v121
	v_mul_f32_e32 v94, 0xbfb8aa3b, v94
	v_exp_f32_e32 v94, v94
	s_nop 0
	v_add_f32_e32 v94, 1.0, v94
	v_rcp_f32_e32 v94, v94
	s_nop 0
	v_mul_f32_e32 v119, v95, v94
	v_cvt_pk_bf16_f32 v94, v96, v97
	v_cvt_pk_bf16_f32 v95, v98, v99
	v_cvt_pk_bf16_f32 v96, v92, v93
	v_lshlrev_b64 v[92:93], 12, v[126:127]
	v_lshl_add_u64 v[92:93], s[44:45], 0, v[92:93]
	v_lshl_add_u64 v[92:93], v[92:93], 0, v[162:163]
	v_cvt_pk_bf16_f32 v97, v118, v119
	global_store_dwordx4 v[92:93], v[94:97], off
	v_add_u32_e32 v243, 0xa0, v164
	v_mad_i64_i32 v[236:237], s[16:17], v243, s4, v[166:167]
	v_lshl_add_u64 v[234:235], v[236:237], 0, s[14:15]
	v_or_b32_e32 v233, 0x80, v154
	v_ashrrev_i32_e32 v232, 31, v233
	v_mov_b32_e32 v228, v233
	v_mov_b32_e32 v229, v232
	v_lshlrev_b64 v[230:231], 1, v[228:229]
	v_lshl_add_u64 v[226:227], v[234:235], 0, v[230:231]
	global_load_dwordx4 v[210:213], v[226:227], off nt
	s_waitcnt vmcnt(17)
; #define GAS __attribute__((address_space(1)))
; __device__ __forceinline__ void unpack8(const v4u v, float (&f)[8]) { f[0] = bflo(v.x); f[1] = bfhi(v.x); f[2] = bflo(v.y); f[3] = bfhi(v.y); f[4] = bflo(v.z); f[5] = bfhi(v.z); f[6] = bflo(v.w); f[7] = bfhi(v.w); }
; __device__ __forceinline__ v4u pack8(const float (&f)[8]) { v4u o; o.x = cvt_pk_bf16(f[0], f[1]); o.y = cvt_pk_bf16(f[2], f[3]); o.z = cvt_pk_bf16(f[4], f[5]); o.w = cvt_pk_bf16(f[6], f[7]); return o; }
; __device__ __forceinline__ float sigmoidf_(float x) { return __builtin_amdgcn_rcpf(1.f + __expf(-x)); }
;     __device__ __forceinline__ void operator()(const f32x4 (&acc)[2][2][4][2], const pg8::Unit& u, int wr, int wc, int fr, int fq) const {
;     ...
;         for (int bj = 0; bj < 2; ++bj) { const int col = col0 + bj * 128;
;             const f32x4 b0 = *(const GAS f32x4*)(bgate + WHICH * DM + col), b1 = *(const GAS f32x4*)(bgate + WHICH * DM + col + 4);
; #pragma unroll
;             for (int aim = 0; aim < 4; ++aim) { const int ai = aim >> 1, mb = (aim & 1) * 2;
;                 v4u gv[4], tv[4];
; #pragma unroll
;                 for (int m = mb; m < mb + 2; ++m) { const int row = row0 + ai * 128 + m * 16;
;                     gv[m] = __builtin_nontemporal_load((const GAS v4u*)(proj + (size_t)row * NPROJ + OFF_GATE + WHICH * DM + col));
;                     if (WHICH == 1) tv[m] = *(const GAS v4u*)(ta + (size_t)row * DM + col); }
; #pragma unroll
;                 for (int m = mb; m < mb + 2; ++m) { const int row = row0 + ai * 128 + m * 16; float g[8]; unpack8(gv[m], g);
;                     const f32x4 a0 = acc[ai][bj][m][0], a1 = acc[ai][bj][m][1]; float r[8];
; #pragma unroll
;                     for (int e = 0; e < 4; ++e) { r[e] = sigmoidf_(g[e] + b0[e]) * a0[e]; r[4 + e] = sigmoidf_(g[4 + e] + b1[e]) * a1[e]; }
;                     if (WHICH == 0) *(GAS v4u*)(ta + (size_t)row * DM + col) = pack8(r);
;                     else { float tf[8]; unpack8(tv[m], tf);
; #pragma unroll
;                         for (int e = 0; e < 8; ++e) r[e] += tf[e];
;                         *(GAS v4u*)(mix + (size_t)row * DM + col) = pack8(r); } }
	v_lshlrev_b32_e32 v98, 16, v224
	v_and_b32_e32 v99, 0xffff0000, v224
	v_lshlrev_b32_e32 v94, 16, v222
	v_add_f32_e32 v94, v104, v94
	v_mul_f32_e32 v94, 0xbfb8aa3b, v94
	v_exp_f32_e32 v94, v94
	v_and_b32_e32 v95, 0xffff0000, v222
	v_lshlrev_b32_e32 v96, 16, v223
	v_lshlrev_b32_e32 v118, 16, v225
	v_add_f32_e32 v94, 1.0, v94
	v_rcp_f32_e32 v94, v94
	v_and_b32_e32 v97, 0xffff0000, v223
	v_and_b32_e32 v119, 0xffff0000, v225
	v_mul_f32_e32 v88, v88, v94
	v_add_f32_e32 v94, v100, v98
	v_mul_f32_e32 v94, 0xbfb8aa3b, v94
	v_exp_f32_e32 v94, v94
	v_add_u32_e32 v98, 0xa0, v164
	v_add_f32_e32 v94, 1.0, v94
	v_rcp_f32_e32 v94, v94
	s_nop 0
	v_mul_f32_e32 v84, v84, v94
	v_add_f32_e32 v94, v105, v95
	v_mul_f32_e32 v94, 0xbfb8aa3b, v94
	v_exp_f32_e32 v94, v94
	s_nop 0
	v_add_f32_e32 v94, 1.0, v94
	v_rcp_f32_e32 v94, v94
	s_nop 0
	v_mul_f32_e32 v89, v89, v94
	v_add_f32_e32 v94, v101, v99
	v_mul_f32_e32 v94, 0xbfb8aa3b, v94
	v_exp_f32_e32 v94, v94
	v_ashrrev_i32_e32 v99, 31, v98
	v_add_f32_e32 v94, 1.0, v94
	v_rcp_f32_e32 v94, v94
	s_nop 0
	v_mul_f32_e32 v85, v85, v94
	v_add_f32_e32 v94, v106, v96
	v_mul_f32_e32 v94, 0xbfb8aa3b, v94
	v_exp_f32_e32 v94, v94
	s_nop 0
	v_add_f32_e32 v94, 1.0, v94
	v_rcp_f32_e32 v94, v94
	s_nop 0
	v_mul_f32_e32 v90, v90, v94
	v_add_f32_e32 v94, v102, v118
	v_mul_f32_e32 v94, 0xbfb8aa3b, v94
	v_exp_f32_e32 v94, v94
	s_nop 0
	v_add_f32_e32 v94, 1.0, v94
	v_rcp_f32_e32 v94, v94
	s_nop 0
	v_mul_f32_e32 v94, v86, v94
	v_add_f32_e32 v86, v107, v97
	v_mul_f32_e32 v86, 0xbfb8aa3b, v86
	v_exp_f32_e32 v86, v86
	s_nop 0
	v_add_f32_e32 v86, 1.0, v86
	v_rcp_f32_e32 v86, v86
	s_nop 0
	v_mul_f32_e32 v91, v91, v86
	v_add_f32_e32 v86, v103, v119
	v_mul_f32_e32 v86, 0xbfb8aa3b, v86
	v_exp_f32_e32 v86, v86
	s_nop 0
	v_add_f32_e32 v86, 1.0, v86
	v_rcp_f32_e32 v86, v86
	s_nop 0
	v_mul_f32_e32 v95, v87, v86
	v_cvt_pk_bf16_f32 v86, v88, v89
	v_cvt_pk_bf16_f32 v87, v90, v91
	v_cvt_pk_bf16_f32 v88, v84, v85
	v_lshlrev_b64 v[84:85], 12, v[114:115]
	v_lshl_add_u64 v[84:85], s[44:45], 0, v[84:85]
	v_lshl_add_u64 v[84:85], v[84:85], 0, v[162:163]
	v_cvt_pk_bf16_f32 v89, v94, v95
	global_store_dwordx4 v[84:85], v[86:89], off
	v_add_u32_e32 v90, 0xb0, v164
	v_ashrrev_i32_e32 v91, 31, v90
	v_mad_i64_i32 v[86:87], s[0:1], v98, s4, v[166:167]
	v_lshl_add_u64 v[86:87], v[86:87], 0, s[14:15]
	v_lshl_add_u64 v[88:89], v[86:87], 0, v[162:163]
	s_nop 0
	v_mad_i64_i32 v[88:89], s[0:1], v90, s4, v[166:167]
	v_lshl_add_u64 v[88:89], v[88:89], 0, s[14:15]
	v_lshl_add_u64 v[114:115], v[88:89], 0, v[162:163]
	s_nop 0
	s_mov_b64 s[0:1], -1
	s_waitcnt vmcnt(17)
	v_lshlrev_b32_e32 v114, 16, v218
	v_and_b32_e32 v94, 0xffff0000, v218
	v_add_f32_e32 v94, v105, v94
	v_mul_f32_e32 v94, 0xbfb8aa3b, v94
	v_exp_f32_e32 v94, v94
	v_lshlrev_b32_e32 v122, 16, v220
	v_and_b32_e32 v96, 0xffff0000, v220
	v_lshlrev_b32_e32 v115, 16, v219
	v_add_f32_e32 v94, 1.0, v94
	v_rcp_f32_e32 v94, v94
	v_lshlrev_b32_e32 v123, 16, v221
	v_add_f32_e32 v114, v104, v114
	v_and_b32_e32 v95, 0xffff0000, v219
	v_mul_f32_e32 v81, v81, v94
	v_add_f32_e32 v94, v101, v96
	v_mul_f32_e32 v94, 0xbfb8aa3b, v94
	v_exp_f32_e32 v94, v94
	v_mul_f32_e32 v114, 0xbfb8aa3b, v114
	v_exp_f32_e32 v114, v114
	v_and_b32_e32 v97, 0xffff0000, v221
	v_add_f32_e32 v94, 1.0, v94
	v_rcp_f32_e32 v94, v94
	v_add_f32_e32 v114, 1.0, v114
	v_rcp_f32_e32 v114, v114
	v_mul_f32_e32 v77, v77, v94
	v_add_f32_e32 v94, v106, v115
	v_mul_f32_e32 v94, 0xbfb8aa3b, v94
	v_exp_f32_e32 v94, v94
	v_mul_f32_e32 v80, v80, v114
	v_add_f32_e32 v114, v100, v122
	v_mul_f32_e32 v114, 0xbfb8aa3b, v114
	v_add_f32_e32 v94, 1.0, v94
	v_rcp_f32_e32 v94, v94
	v_exp_f32_e32 v114, v114
	v_cvt_pk_bf16_f32 v80, v80, v81
	v_mul_f32_e32 v82, v82, v94
	v_add_f32_e32 v94, v102, v123
	v_mul_f32_e32 v94, 0xbfb8aa3b, v94
	v_exp_f32_e32 v94, v94
	v_add_f32_e32 v114, 1.0, v114
	v_rcp_f32_e32 v114, v114
	v_add_f32_e32 v94, 1.0, v94
	v_rcp_f32_e32 v94, v94
	v_mul_f32_e32 v76, v76, v114
	v_mul_f32_e32 v78, v78, v94
	v_add_f32_e32 v94, v107, v95
	v_mul_f32_e32 v94, 0xbfb8aa3b, v94
	v_exp_f32_e32 v94, v94
	s_waitcnt vmcnt(16)
	v_and_b32_e32 v95, 0xffff0000, v217
	v_add_f32_e32 v94, 1.0, v94
	v_rcp_f32_e32 v94, v94
	s_nop 0
	v_mul_f32_e32 v83, v83, v94
	v_add_f32_e32 v94, v103, v97
	v_mul_f32_e32 v94, 0xbfb8aa3b, v94
	v_exp_f32_e32 v94, v94
	v_cvt_pk_bf16_f32 v81, v82, v83
	v_cvt_pk_bf16_f32 v82, v76, v77
	v_lshlrev_b64 v[76:77], 12, v[98:99]
	v_add_f32_e32 v94, 1.0, v94
	v_rcp_f32_e32 v94, v94
	v_lshl_add_u64 v[76:77], s[44:45], 0, v[76:77]
	v_mul_f32_e32 v79, v79, v94
	v_cvt_pk_bf16_f32 v83, v78, v79
	v_lshl_add_u64 v[78:79], v[76:77], 0, v[162:163]
	v_lshlrev_b32_e32 v76, 16, v214
	v_add_f32_e32 v76, v104, v76
	v_mul_f32_e32 v76, 0xbfb8aa3b, v76
	v_exp_f32_e32 v76, v76
	global_store_dwordx4 v[78:79], v[80:83], off
	v_and_b32_e32 v77, 0xffff0000, v214
	v_lshlrev_b32_e32 v94, 16, v217
	v_add_f32_e32 v76, 1.0, v76
	v_rcp_f32_e32 v76, v76
	v_lshlrev_b32_e32 v82, 16, v216
	v_and_b32_e32 v83, 0xffff0000, v216
	v_lshlrev_b32_e32 v80, 16, v215
	v_mul_f32_e32 v72, v72, v76
	v_add_f32_e32 v76, v100, v82
	v_mul_f32_e32 v76, 0xbfb8aa3b, v76
	v_exp_f32_e32 v76, v76
	v_and_b32_e32 v81, 0xffff0000, v215
	v_add_f32_e32 v76, 1.0, v76
	v_rcp_f32_e32 v76, v76
	s_nop 0
	v_mul_f32_e32 v76, v68, v76
	v_add_f32_e32 v68, v105, v77
	v_mul_f32_e32 v68, 0xbfb8aa3b, v68
	v_exp_f32_e32 v68, v68
	s_nop 0
	v_add_f32_e32 v68, 1.0, v68
	v_rcp_f32_e32 v68, v68
	s_nop 0
	v_mul_f32_e32 v68, v73, v68
	v_add_f32_e32 v73, v101, v83
	v_mul_f32_e32 v73, 0xbfb8aa3b, v73
	v_exp_f32_e32 v73, v73
	v_cvt_pk_bf16_f32 v68, v72, v68
	s_nop 0
	v_add_f32_e32 v73, 1.0, v73
	v_rcp_f32_e32 v73, v73
	s_nop 0
	v_mul_f32_e32 v73, v69, v73
	v_add_f32_e32 v69, v106, v80
	v_mul_f32_e32 v69, 0xbfb8aa3b, v69
	v_exp_f32_e32 v69, v69
	v_or_b32_e32 v80, 0x80, v154
	v_add_f32_e32 v69, 1.0, v69
	v_rcp_f32_e32 v69, v69
	s_nop 0
	v_mul_f32_e32 v69, v74, v69
	v_add_f32_e32 v74, v102, v94
	v_mul_f32_e32 v74, 0xbfb8aa3b, v74
	v_exp_f32_e32 v74, v74
	s_nop 0
	v_add_f32_e32 v74, 1.0, v74
	v_rcp_f32_e32 v74, v74
	s_nop 0
	v_mul_f32_e32 v74, v70, v74
	v_add_f32_e32 v70, v107, v81
	v_mul_f32_e32 v70, 0xbfb8aa3b, v70
	v_exp_f32_e32 v70, v70
	v_ashrrev_i32_e32 v81, 31, v80
	v_lshlrev_b64 v[80:81], 1, v[80:81]
	v_lshl_add_u64 v[82:83], v[160:161], 0, v[80:81]
	v_add_f32_e32 v70, 1.0, v70
	v_rcp_f32_e32 v70, v70
	s_nop 0
	v_mul_f32_e32 v70, v75, v70
	v_add_f32_e32 v75, v103, v95
	v_mul_f32_e32 v75, 0xbfb8aa3b, v75
	v_exp_f32_e32 v75, v75
	v_cvt_pk_bf16_f32 v69, v69, v70
	v_cvt_pk_bf16_f32 v70, v76, v73
	v_lshlrev_b64 v[72:73], 12, v[90:91]
	v_add_f32_e32 v75, 1.0, v75
	v_rcp_f32_e32 v75, v75
	v_lshl_add_u64 v[72:73], s[44:45], 0, v[72:73]
	v_lshl_add_u64 v[76:77], v[72:73], 0, v[162:163]
	v_mul_f32_e32 v71, v71, v75
	v_cvt_pk_bf16_f32 v71, v74, v71
	global_store_dwordx4 v[76:77], v[68:71], off
	s_nop 0
	s_nop 0
	s_nop 0
	s_nop 0
	v_lshl_add_u64 v[82:83], v[158:159], 0, v[80:81]
	s_nop 0
	s_waitcnt vmcnt(15)
; #define GAS __attribute__((address_space(1)))
; __device__ __forceinline__ void unpack8(const v4u v, float (&f)[8]) { f[0] = bflo(v.x); f[1] = bfhi(v.x); f[2] = bflo(v.y); f[3] = bfhi(v.y); f[4] = bflo(v.z); f[5] = bfhi(v.z); f[6] = bflo(v.w); f[7] = bfhi(v.w); }
; __device__ __forceinline__ v4u pack8(const float (&f)[8]) { v4u o; o.x = cvt_pk_bf16(f[0], f[1]); o.y = cvt_pk_bf16(f[2], f[3]); o.z = cvt_pk_bf16(f[4], f[5]); o.w = cvt_pk_bf16(f[6], f[7]); return o; }
; __device__ __forceinline__ float sigmoidf_(float x) { return __builtin_amdgcn_rcpf(1.f + __expf(-x)); }
;     __device__ __forceinline__ void operator()(const f32x4 (&acc)[2][2][4][2], const pg8::Unit& u, int wr, int wc, int fr, int fq) const {
;     ...
;         for (int bj = 0; bj < 2; ++bj) { const int col = col0 + bj * 128;
;             const f32x4 b0 = *(const GAS f32x4*)(bgate + WHICH * DM + col), b1 = *(const GAS f32x4*)(bgate + WHICH * DM + col + 4);
; #pragma unroll
;             for (int aim = 0; aim < 4; ++aim) { const int ai = aim >> 1, mb = (aim & 1) * 2;
;                 v4u gv[4], tv[4];
; #pragma unroll
;                 for (int m = mb; m < mb + 2; ++m) { const int row = row0 + ai * 128 + m * 16;
;                     gv[m] = __builtin_nontemporal_load((const GAS v4u*)(proj + (size_t)row * NPROJ + OFF_GATE + WHICH * DM + col));
;                     if (WHICH == 1) tv[m] = *(const GAS v4u*)(ta + (size_t)row * DM + col); }
; #pragma unroll
;                 for (int m = mb; m < mb + 2; ++m) { const int row = row0 + ai * 128 + m * 16; float g[8]; unpack8(gv[m], g);
;                     const f32x4 a0 = acc[ai][bj][m][0], a1 = acc[ai][bj][m][1]; float r[8];
; #pragma unroll
;                     for (int e = 0; e < 4; ++e) { r[e] = sigmoidf_(g[e] + b0[e]) * a0[e]; r[4 + e] = sigmoidf_(g[4 + e] + b1[e]) * a1[e]; }
;                     if (WHICH == 0) *(GAS v4u*)(ta + (size_t)row * DM + col) = pack8(r);
;                     else { float tf[8]; unpack8(tv[m], tf);
; #pragma unroll
;                         for (int e = 0; e < 8; ++e) r[e] += tf[e];
;                         *(GAS v4u*)(mix + (size_t)row * DM + col) = pack8(r); } }
	v_lshlrev_b32_e32 v82, 16, v202
	v_add_f32_e32 v82, v244, v82
	v_mul_f32_e32 v82, 0xbfb8aa3b, v82
	v_exp_f32_e32 v82, v82
	v_and_b32_e32 v83, 0xffff0000, v202
	v_lshlrev_b32_e32 v94, 16, v204
	v_lshlrev_b32_e32 v90, 16, v203
	v_add_f32_e32 v82, 1.0, v82
	v_rcp_f32_e32 v82, v82
	v_and_b32_e32 v91, 0xffff0000, v203
	v_and_b32_e32 v95, 0xffff0000, v204
	v_lshlrev_b32_e32 v96, 16, v205
	v_mul_f32_e32 v64, v64, v82
	v_add_f32_e32 v82, v248, v94
	v_mul_f32_e32 v82, 0xbfb8aa3b, v82
	v_exp_f32_e32 v82, v82
	v_and_b32_e32 v97, 0xffff0000, v205
	v_add_f32_e32 v82, 1.0, v82
	v_rcp_f32_e32 v82, v82
	s_nop 0
	v_mul_f32_e32 v82, v60, v82
	v_add_f32_e32 v60, v245, v83
	v_mul_f32_e32 v60, 0xbfb8aa3b, v60
	v_exp_f32_e32 v60, v60
	s_nop 0
	v_add_f32_e32 v60, 1.0, v60
	v_rcp_f32_e32 v60, v60
	s_nop 0
	v_mul_f32_e32 v60, v65, v60
	v_add_f32_e32 v65, v249, v95
	v_mul_f32_e32 v65, 0xbfb8aa3b, v65
	v_exp_f32_e32 v65, v65
	v_cvt_pk_bf16_f32 v60, v64, v60
	s_waitcnt vmcnt(14)
	v_lshlrev_b32_e32 v64, 16, v200
	v_add_f32_e32 v65, 1.0, v65
	v_rcp_f32_e32 v65, v65
	s_nop 0
	v_mul_f32_e32 v65, v61, v65
	v_add_f32_e32 v61, v246, v90
	v_mul_f32_e32 v61, 0xbfb8aa3b, v61
	v_exp_f32_e32 v61, v61
	s_nop 0
	v_add_f32_e32 v61, 1.0, v61
	v_rcp_f32_e32 v61, v61
	s_nop 0
	v_mul_f32_e32 v61, v66, v61
	v_add_f32_e32 v66, v250, v96
	v_mul_f32_e32 v66, 0xbfb8aa3b, v66
	v_exp_f32_e32 v66, v66
	s_nop 0
	v_add_f32_e32 v66, 1.0, v66
	v_rcp_f32_e32 v66, v66
	s_nop 0
	v_mul_f32_e32 v66, v62, v66
	v_add_f32_e32 v62, v247, v91
	v_mul_f32_e32 v62, 0xbfb8aa3b, v62
	v_exp_f32_e32 v62, v62
	s_nop 0
	v_add_f32_e32 v62, 1.0, v62
	v_rcp_f32_e32 v62, v62
	s_nop 0
	v_mul_f32_e32 v62, v67, v62
	v_add_f32_e32 v67, v251, v97
	v_mul_f32_e32 v67, 0xbfb8aa3b, v67
	v_exp_f32_e32 v67, v67
	v_cvt_pk_bf16_f32 v61, v61, v62
	v_cvt_pk_bf16_f32 v62, v82, v65
	v_and_b32_e32 v65, 0xffff0000, v200
	v_add_f32_e32 v67, 1.0, v67
	v_rcp_f32_e32 v67, v67
	s_nop 0
	v_mul_f32_e32 v63, v63, v67
	v_cvt_pk_bf16_f32 v63, v66, v63
	global_store_dwordx4 v[136:137], v[60:63], off offset:256
	v_lshlrev_b32_e32 v66, 16, v201
	v_and_b32_e32 v67, 0xffff0000, v201
	v_lshlrev_b32_e32 v60, 16, v198
	v_add_f32_e32 v60, v244, v60
	v_mul_f32_e32 v60, 0xbfb8aa3b, v60
	v_exp_f32_e32 v60, v60
	v_and_b32_e32 v61, 0xffff0000, v198
	v_lshlrev_b32_e32 v62, 16, v199
	v_and_b32_e32 v63, 0xffff0000, v199
	v_add_f32_e32 v60, 1.0, v60
	v_rcp_f32_e32 v60, v60
	s_nop 0
	v_mul_f32_e32 v56, v56, v60
	v_add_f32_e32 v60, v248, v64
	v_mul_f32_e32 v60, 0xbfb8aa3b, v60
	v_exp_f32_e32 v60, v60
	s_nop 0
	v_add_f32_e32 v60, 1.0, v60
	v_rcp_f32_e32 v60, v60
	s_nop 0
	v_mul_f32_e32 v60, v52, v60
	v_add_f32_e32 v52, v245, v61
	v_mul_f32_e32 v52, 0xbfb8aa3b, v52
	v_exp_f32_e32 v52, v52
	s_nop 0
	v_add_f32_e32 v52, 1.0, v52
	v_rcp_f32_e32 v52, v52
	s_nop 0
	v_mul_f32_e32 v52, v57, v52
	v_add_f32_e32 v57, v249, v65
	v_mul_f32_e32 v57, 0xbfb8aa3b, v57
	v_exp_f32_e32 v57, v57
	v_cvt_pk_bf16_f32 v52, v56, v52
	s_nop 0
	v_add_f32_e32 v57, 1.0, v57
	v_rcp_f32_e32 v57, v57
	s_nop 0
	v_mul_f32_e32 v57, v53, v57
	v_add_f32_e32 v53, v246, v62
	v_mul_f32_e32 v53, 0xbfb8aa3b, v53
	v_exp_f32_e32 v53, v53
	s_nop 0
	v_add_f32_e32 v53, 1.0, v53
	v_rcp_f32_e32 v53, v53
	s_nop 0
	v_mul_f32_e32 v53, v58, v53
	v_add_f32_e32 v58, v250, v66
	v_mul_f32_e32 v58, 0xbfb8aa3b, v58
	v_exp_f32_e32 v58, v58
	s_nop 0
	v_add_f32_e32 v58, 1.0, v58
	v_rcp_f32_e32 v58, v58
	s_nop 0
	v_mul_f32_e32 v58, v54, v58
	v_add_f32_e32 v54, v247, v63
	v_mul_f32_e32 v54, 0xbfb8aa3b, v54
	v_exp_f32_e32 v54, v54
	s_nop 0
	v_add_f32_e32 v54, 1.0, v54
	v_rcp_f32_e32 v54, v54
	s_nop 0
	v_mul_f32_e32 v54, v59, v54
	v_add_f32_e32 v59, v251, v67
	v_mul_f32_e32 v59, 0xbfb8aa3b, v59
	v_exp_f32_e32 v59, v59
	v_cvt_pk_bf16_f32 v53, v53, v54
	v_cvt_pk_bf16_f32 v54, v60, v57
	v_lshl_add_u64 v[56:57], v[132:133], 0, v[80:81]
	v_add_f32_e32 v59, 1.0, v59
	v_rcp_f32_e32 v59, v59
	s_nop 0
	v_mul_f32_e32 v55, v55, v59
	v_cvt_pk_bf16_f32 v55, v58, v55
	global_store_dwordx4 v[128:129], v[52:55], off offset:256
	s_nop 0
	s_nop 0
	v_lshl_add_u64 v[52:53], v[130:131], 0, v[80:81]
	s_nop 0
	s_waitcnt vmcnt(13)
	v_lshlrev_b32_e32 v60, 16, v186
	v_add_f32_e32 v60, v244, v60
	v_mul_f32_e32 v60, 0xbfb8aa3b, v60
	v_exp_f32_e32 v60, v60
	v_lshlrev_b32_e32 v62, 16, v188
	v_and_b32_e32 v52, 0xffff0000, v186
	v_and_b32_e32 v54, 0xffff0000, v188
	v_add_f32_e32 v60, 1.0, v60
	v_rcp_f32_e32 v60, v60
	v_lshlrev_b32_e32 v61, 16, v187
	v_lshlrev_b32_e32 v63, 16, v189
	v_and_b32_e32 v53, 0xffff0000, v187
	v_mul_f32_e32 v48, v48, v60
	v_add_f32_e32 v60, v248, v62
	v_mul_f32_e32 v60, 0xbfb8aa3b, v60
	v_exp_f32_e32 v60, v60
	v_and_b32_e32 v55, 0xffff0000, v189
	v_add_f32_e32 v60, 1.0, v60
	v_rcp_f32_e32 v60, v60
	s_nop 0
	v_mul_f32_e32 v60, v44, v60
	v_add_f32_e32 v44, v245, v52
	v_mul_f32_e32 v44, 0xbfb8aa3b, v44
	v_exp_f32_e32 v44, v44
	s_nop 0
	v_add_f32_e32 v44, 1.0, v44
	v_rcp_f32_e32 v44, v44
	s_nop 0
	v_mul_f32_e32 v44, v49, v44
	v_add_f32_e32 v49, v249, v54
	v_mul_f32_e32 v49, 0xbfb8aa3b, v49
	v_exp_f32_e32 v49, v49
	v_cvt_pk_bf16_f32 v44, v48, v44
	v_lshlrev_b32_e32 v48, 16, v192
	v_add_f32_e32 v49, 1.0, v49
	v_rcp_f32_e32 v49, v49
	s_nop 0
	v_mul_f32_e32 v49, v45, v49
	v_add_f32_e32 v45, v246, v61
	v_mul_f32_e32 v45, 0xbfb8aa3b, v45
	v_exp_f32_e32 v45, v45
	s_nop 0
	v_add_f32_e32 v45, 1.0, v45
	v_rcp_f32_e32 v45, v45
	s_nop 0
	v_mul_f32_e32 v45, v50, v45
	v_add_f32_e32 v50, v250, v63
	v_mul_f32_e32 v50, 0xbfb8aa3b, v50
	v_exp_f32_e32 v50, v50
	s_nop 0
	v_add_f32_e32 v50, 1.0, v50
	v_rcp_f32_e32 v50, v50
	s_nop 0
	v_mul_f32_e32 v50, v46, v50
	v_add_f32_e32 v46, v247, v53
	v_mul_f32_e32 v46, 0xbfb8aa3b, v46
	v_exp_f32_e32 v46, v46
	s_nop 0
; #define GAS __attribute__((address_space(1)))
; __device__ __forceinline__ void unpack8(const v4u v, float (&f)[8]) { f[0] = bflo(v.x); f[1] = bfhi(v.x); f[2] = bflo(v.y); f[3] = bfhi(v.y); f[4] = bflo(v.z); f[5] = bfhi(v.z); f[6] = bflo(v.w); f[7] = bfhi(v.w); }
; __device__ __forceinline__ v4u pack8(const float (&f)[8]) { v4u o; o.x = cvt_pk_bf16(f[0], f[1]); o.y = cvt_pk_bf16(f[2], f[3]); o.z = cvt_pk_bf16(f[4], f[5]); o.w = cvt_pk_bf16(f[6], f[7]); return o; }
; __device__ __forceinline__ float sigmoidf_(float x) { return __builtin_amdgcn_rcpf(1.f + __expf(-x)); }
;     __device__ __forceinline__ void operator()(const f32x4 (&acc)[2][2][4][2], const pg8::Unit& u, int wr, int wc, int fr, int fq) const {
;     ...
;         for (int bj = 0; bj < 2; ++bj) { const int col = col0 + bj * 128;
;             const f32x4 b0 = *(const GAS f32x4*)(bgate + WHICH * DM + col), b1 = *(const GAS f32x4*)(bgate + WHICH * DM + col + 4);
; #pragma unroll
;             for (int aim = 0; aim < 4; ++aim) { const int ai = aim >> 1, mb = (aim & 1) * 2;
;                 v4u gv[4], tv[4];
; #pragma unroll
;                 for (int m = mb; m < mb + 2; ++m) { const int row = row0 + ai * 128 + m * 16;
;                     gv[m] = __builtin_nontemporal_load((const GAS v4u*)(proj + (size_t)row * NPROJ + OFF_GATE + WHICH * DM + col));
;                     if (WHICH == 1) tv[m] = *(const GAS v4u*)(ta + (size_t)row * DM + col); }
; #pragma unroll
;                 for (int m = mb; m < mb + 2; ++m) { const int row = row0 + ai * 128 + m * 16; float g[8]; unpack8(gv[m], g);
;                     const f32x4 a0 = acc[ai][bj][m][0], a1 = acc[ai][bj][m][1]; float r[8];
; #pragma unroll
;                     for (int e = 0; e < 4; ++e) { r[e] = sigmoidf_(g[e] + b0[e]) * a0[e]; r[4 + e] = sigmoidf_(g[4 + e] + b1[e]) * a1[e]; }
;                     if (WHICH == 0) *(GAS v4u*)(ta + (size_t)row * DM + col) = pack8(r);
;                     else { float tf[8]; unpack8(tv[m], tf);
; #pragma unroll
;                         for (int e = 0; e < 8; ++e) r[e] += tf[e];
;                         *(GAS v4u*)(mix + (size_t)row * DM + col) = pack8(r); } }
	v_add_f32_e32 v46, 1.0, v46
	v_rcp_f32_e32 v46, v46
	s_nop 0
	v_mul_f32_e32 v46, v51, v46
	v_add_f32_e32 v51, v251, v55
	v_mul_f32_e32 v51, 0xbfb8aa3b, v51
	v_exp_f32_e32 v51, v51
	v_cvt_pk_bf16_f32 v45, v45, v46
	v_cvt_pk_bf16_f32 v46, v60, v49
	v_and_b32_e32 v49, 0xffff0000, v192
	v_add_f32_e32 v51, 1.0, v51
	v_rcp_f32_e32 v51, v51
	s_nop 0
	v_mul_f32_e32 v47, v47, v51
	v_cvt_pk_bf16_f32 v47, v50, v47
	global_store_dwordx4 v[116:117], v[44:47], off offset:256
	v_lshlrev_b32_e32 v50, 16, v193
	v_and_b32_e32 v51, 0xffff0000, v193
	v_lshlrev_b32_e32 v44, 16, v190
	v_add_f32_e32 v44, v244, v44
	v_mul_f32_e32 v44, 0xbfb8aa3b, v44
	v_exp_f32_e32 v44, v44
	v_and_b32_e32 v45, 0xffff0000, v190
	v_lshlrev_b32_e32 v46, 16, v191
	v_and_b32_e32 v47, 0xffff0000, v191
	v_add_f32_e32 v44, 1.0, v44
	v_rcp_f32_e32 v44, v44
	s_nop 0
	v_mul_f32_e32 v40, v40, v44
	v_add_f32_e32 v44, v248, v48
	v_mul_f32_e32 v44, 0xbfb8aa3b, v44
	v_exp_f32_e32 v44, v44
	s_nop 0
	v_add_f32_e32 v44, 1.0, v44
	v_rcp_f32_e32 v44, v44
	s_nop 0
	v_mul_f32_e32 v44, v36, v44
	v_add_f32_e32 v36, v245, v45
	v_mul_f32_e32 v36, 0xbfb8aa3b, v36
	v_exp_f32_e32 v36, v36
	s_nop 0
	v_add_f32_e32 v36, 1.0, v36
	v_rcp_f32_e32 v36, v36
	s_nop 0
	v_mul_f32_e32 v36, v41, v36
	v_add_f32_e32 v41, v249, v49
	v_mul_f32_e32 v41, 0xbfb8aa3b, v41
	v_exp_f32_e32 v41, v41
	v_cvt_pk_bf16_f32 v36, v40, v36
	s_nop 0
	v_add_f32_e32 v41, 1.0, v41
	v_rcp_f32_e32 v41, v41
	s_nop 0
	v_mul_f32_e32 v41, v37, v41
	v_add_f32_e32 v37, v246, v46
	v_mul_f32_e32 v37, 0xbfb8aa3b, v37
	v_exp_f32_e32 v37, v37
	s_nop 0
	v_add_f32_e32 v37, 1.0, v37
	v_rcp_f32_e32 v37, v37
	s_nop 0
	v_mul_f32_e32 v37, v42, v37
	v_add_f32_e32 v42, v250, v50
	v_mul_f32_e32 v42, 0xbfb8aa3b, v42
	v_exp_f32_e32 v42, v42
	s_nop 0
	v_add_f32_e32 v42, 1.0, v42
	v_rcp_f32_e32 v42, v42
	s_nop 0
	v_mul_f32_e32 v42, v38, v42
	v_add_f32_e32 v38, v247, v47
	v_mul_f32_e32 v38, 0xbfb8aa3b, v38
	v_exp_f32_e32 v38, v38
	s_nop 0
	v_add_f32_e32 v38, 1.0, v38
	v_rcp_f32_e32 v38, v38
	s_nop 0
	v_mul_f32_e32 v38, v43, v38
	v_add_f32_e32 v43, v251, v51
	v_mul_f32_e32 v43, 0xbfb8aa3b, v43
	v_exp_f32_e32 v43, v43
	v_cvt_pk_bf16_f32 v37, v37, v38
	v_cvt_pk_bf16_f32 v38, v44, v41
	v_lshl_add_u64 v[40:41], v[112:113], 0, v[80:81]
	v_add_f32_e32 v43, 1.0, v43
	v_rcp_f32_e32 v43, v43
	s_nop 0
	v_mul_f32_e32 v39, v39, v43
	v_cvt_pk_bf16_f32 v39, v42, v39
	global_store_dwordx4 v[108:109], v[36:39], off offset:256
	s_nop 0
	s_nop 0
	v_lshl_add_u64 v[36:37], v[110:111], 0, v[80:81]
	s_nop 0
	s_waitcnt vmcnt(11)
	v_lshlrev_b32_e32 v44, 16, v140
	v_add_f32_e32 v44, v244, v44
	v_mul_f32_e32 v44, 0xbfb8aa3b, v44
	v_exp_f32_e32 v44, v44
	v_lshlrev_b32_e32 v46, 16, v142
	v_and_b32_e32 v36, 0xffff0000, v140
	v_and_b32_e32 v38, 0xffff0000, v142
	v_add_f32_e32 v44, 1.0, v44
	v_rcp_f32_e32 v44, v44
	v_lshlrev_b32_e32 v45, 16, v141
	v_lshlrev_b32_e32 v47, 16, v143
	v_and_b32_e32 v37, 0xffff0000, v141
	v_mul_f32_e32 v32, v32, v44
	v_add_f32_e32 v44, v248, v46
	v_mul_f32_e32 v44, 0xbfb8aa3b, v44
	v_exp_f32_e32 v44, v44
	v_and_b32_e32 v39, 0xffff0000, v143
	v_add_f32_e32 v44, 1.0, v44
	v_rcp_f32_e32 v44, v44
	s_nop 0
	v_mul_f32_e32 v44, v28, v44
	v_add_f32_e32 v28, v245, v36
	v_mul_f32_e32 v28, 0xbfb8aa3b, v28
	v_exp_f32_e32 v28, v28
	s_nop 0
	v_add_f32_e32 v28, 1.0, v28
	v_rcp_f32_e32 v28, v28
	s_nop 0
	v_mul_f32_e32 v28, v33, v28
	v_add_f32_e32 v33, v249, v38
	v_mul_f32_e32 v33, 0xbfb8aa3b, v33
	v_exp_f32_e32 v33, v33
	v_cvt_pk_bf16_f32 v28, v32, v28
	v_lshlrev_b32_e32 v32, 16, v196
	v_add_f32_e32 v33, 1.0, v33
	v_rcp_f32_e32 v33, v33
	s_nop 0
	v_mul_f32_e32 v33, v29, v33
	v_add_f32_e32 v29, v246, v45
	v_mul_f32_e32 v29, 0xbfb8aa3b, v29
	v_exp_f32_e32 v29, v29
	s_nop 0
	v_add_f32_e32 v29, 1.0, v29
	v_rcp_f32_e32 v29, v29
	s_nop 0
	v_mul_f32_e32 v29, v34, v29
	v_add_f32_e32 v34, v250, v47
	v_mul_f32_e32 v34, 0xbfb8aa3b, v34
	v_exp_f32_e32 v34, v34
	s_nop 0
	v_add_f32_e32 v34, 1.0, v34
	v_rcp_f32_e32 v34, v34
	s_nop 0
	v_mul_f32_e32 v34, v30, v34
	v_add_f32_e32 v30, v247, v37
	v_mul_f32_e32 v30, 0xbfb8aa3b, v30
	v_exp_f32_e32 v30, v30
	s_nop 0
	v_add_f32_e32 v30, 1.0, v30
	v_rcp_f32_e32 v30, v30
	s_nop 0
	v_mul_f32_e32 v30, v35, v30
	v_add_f32_e32 v35, v251, v39
	v_mul_f32_e32 v35, 0xbfb8aa3b, v35
	v_exp_f32_e32 v35, v35
	v_cvt_pk_bf16_f32 v29, v29, v30
	v_cvt_pk_bf16_f32 v30, v44, v33
	v_and_b32_e32 v33, 0xffff0000, v196
	v_add_f32_e32 v35, 1.0, v35
	v_rcp_f32_e32 v35, v35
	s_nop 0
	v_mul_f32_e32 v31, v31, v35
	v_cvt_pk_bf16_f32 v31, v34, v31
	global_store_dwordx4 v[92:93], v[28:31], off offset:256
	v_lshlrev_b32_e32 v34, 16, v197
	v_and_b32_e32 v35, 0xffff0000, v197
	v_lshlrev_b32_e32 v28, 16, v194
	v_add_f32_e32 v28, v244, v28
	v_mul_f32_e32 v28, 0xbfb8aa3b, v28
	v_exp_f32_e32 v28, v28
	v_and_b32_e32 v29, 0xffff0000, v194
	v_lshlrev_b32_e32 v30, 16, v195
	v_and_b32_e32 v31, 0xffff0000, v195
	v_add_f32_e32 v28, 1.0, v28
	v_rcp_f32_e32 v28, v28
	s_nop 0
	v_mul_f32_e32 v24, v24, v28
	v_add_f32_e32 v28, v248, v32
	v_mul_f32_e32 v28, 0xbfb8aa3b, v28
	v_exp_f32_e32 v28, v28
	s_nop 0
	v_add_f32_e32 v28, 1.0, v28
	v_rcp_f32_e32 v28, v28
	s_nop 0
	v_mul_f32_e32 v28, v20, v28
	v_add_f32_e32 v20, v245, v29
	v_mul_f32_e32 v20, 0xbfb8aa3b, v20
	v_exp_f32_e32 v20, v20
	s_nop 0
	v_add_f32_e32 v20, 1.0, v20
	v_rcp_f32_e32 v20, v20
	s_nop 0
	v_mul_f32_e32 v20, v25, v20
	v_add_f32_e32 v25, v249, v33
	v_mul_f32_e32 v25, 0xbfb8aa3b, v25
	v_exp_f32_e32 v25, v25
	v_cvt_pk_bf16_f32 v20, v24, v20
	s_nop 0
	v_add_f32_e32 v25, 1.0, v25
	v_rcp_f32_e32 v25, v25
	s_nop 0
	v_mul_f32_e32 v25, v21, v25
	v_add_f32_e32 v21, v246, v30
	v_mul_f32_e32 v21, 0xbfb8aa3b, v21
	v_exp_f32_e32 v21, v21
	s_nop 0
	v_add_f32_e32 v21, 1.0, v21
	v_rcp_f32_e32 v21, v21
	s_nop 0
	v_mul_f32_e32 v21, v26, v21
	v_add_f32_e32 v26, v250, v34
	v_mul_f32_e32 v26, 0xbfb8aa3b, v26
	v_exp_f32_e32 v26, v26
	s_nop 0
	v_add_f32_e32 v26, 1.0, v26
	v_rcp_f32_e32 v26, v26
	s_nop 0
	v_mul_f32_e32 v26, v22, v26
	v_add_f32_e32 v22, v247, v31
	v_mul_f32_e32 v22, 0xbfb8aa3b, v22
	v_exp_f32_e32 v22, v22
	s_nop 0
	v_add_f32_e32 v22, 1.0, v22
	v_rcp_f32_e32 v22, v22
	s_nop 0
	v_mul_f32_e32 v22, v27, v22
	v_add_f32_e32 v27, v251, v35
	v_mul_f32_e32 v27, 0xbfb8aa3b, v27
	v_exp_f32_e32 v27, v27
	v_cvt_pk_bf16_f32 v21, v21, v22
	v_cvt_pk_bf16_f32 v22, v28, v25
	v_lshl_add_u64 v[24:25], v[88:89], 0, v[80:81]
	v_add_f32_e32 v27, 1.0, v27
	v_rcp_f32_e32 v27, v27
	s_nop 0
	v_mul_f32_e32 v23, v23, v27
	v_cvt_pk_bf16_f32 v23, v26, v23
	global_store_dwordx4 v[84:85], v[20:23], off offset:256
	s_nop 0
	s_nop 0
	v_lshl_add_u64 v[20:21], v[86:87], 0, v[80:81]
	s_nop 0
	s_waitcnt vmcnt(9)
; #define GAS __attribute__((address_space(1)))
; __device__ __forceinline__ void unpack8(const v4u v, float (&f)[8]) { f[0] = bflo(v.x); f[1] = bfhi(v.x); f[2] = bflo(v.y); f[3] = bfhi(v.y); f[4] = bflo(v.z); f[5] = bfhi(v.z); f[6] = bflo(v.w); f[7] = bfhi(v.w); }
; __device__ __forceinline__ v4u pack8(const float (&f)[8]) { v4u o; o.x = cvt_pk_bf16(f[0], f[1]); o.y = cvt_pk_bf16(f[2], f[3]); o.z = cvt_pk_bf16(f[4], f[5]); o.w = cvt_pk_bf16(f[6], f[7]); return o; }
; __device__ __forceinline__ float sigmoidf_(float x) { return __builtin_amdgcn_rcpf(1.f + __expf(-x)); }
;     __device__ __forceinline__ void operator()(const f32x4 (&acc)[2][2][4][2], const pg8::Unit& u, int wr, int wc, int fr, int fq) const {
;     ...
;         for (int bj = 0; bj < 2; ++bj) { const int col = col0 + bj * 128;
;             const f32x4 b0 = *(const GAS f32x4*)(bgate + WHICH * DM + col), b1 = *(const GAS f32x4*)(bgate + WHICH * DM + col + 4);
; #pragma unroll
;             for (int aim = 0; aim < 4; ++aim) { const int ai = aim >> 1, mb = (aim & 1) * 2;
;                 v4u gv[4], tv[4];
; #pragma unroll
;                 for (int m = mb; m < mb + 2; ++m) { const int row = row0 + ai * 128 + m * 16;
;                     gv[m] = __builtin_nontemporal_load((const GAS v4u*)(proj + (size_t)row * NPROJ + OFF_GATE + WHICH * DM + col));
;                     if (WHICH == 1) tv[m] = *(const GAS v4u*)(ta + (size_t)row * DM + col); }
; #pragma unroll
;                 for (int m = mb; m < mb + 2; ++m) { const int row = row0 + ai * 128 + m * 16; float g[8]; unpack8(gv[m], g);
;                     const f32x4 a0 = acc[ai][bj][m][0], a1 = acc[ai][bj][m][1]; float r[8];
; #pragma unroll
;                     for (int e = 0; e < 4; ++e) { r[e] = sigmoidf_(g[e] + b0[e]) * a0[e]; r[4 + e] = sigmoidf_(g[4 + e] + b1[e]) * a1[e]; }
;                     if (WHICH == 0) *(GAS v4u*)(ta + (size_t)row * DM + col) = pack8(r);
;                     else { float tf[8]; unpack8(tv[m], tf);
; #pragma unroll
;                         for (int e = 0; e < 8; ++e) r[e] += tf[e];
;                         *(GAS v4u*)(mix + (size_t)row * DM + col) = pack8(r); } }
;             }
;         }
;     }
	v_lshlrev_b32_e32 v28, 16, v210
	v_add_f32_e32 v28, v244, v28
	v_mul_f32_e32 v28, 0xbfb8aa3b, v28
	v_exp_f32_e32 v28, v28
	v_lshlrev_b32_e32 v30, 16, v212
	v_and_b32_e32 v20, 0xffff0000, v210
	v_and_b32_e32 v22, 0xffff0000, v212
	v_add_f32_e32 v28, 1.0, v28
	v_rcp_f32_e32 v28, v28
	v_lshlrev_b32_e32 v29, 16, v211
	v_lshlrev_b32_e32 v31, 16, v213
	v_and_b32_e32 v21, 0xffff0000, v211
	v_mul_f32_e32 v16, v16, v28
	v_add_f32_e32 v28, v248, v30
	v_mul_f32_e32 v28, 0xbfb8aa3b, v28
	v_exp_f32_e32 v28, v28
	v_and_b32_e32 v23, 0xffff0000, v213
	v_add_f32_e32 v28, 1.0, v28
	v_rcp_f32_e32 v28, v28
	s_nop 0
	v_mul_f32_e32 v28, v12, v28
	v_add_f32_e32 v12, v245, v20
	v_mul_f32_e32 v12, 0xbfb8aa3b, v12
	v_exp_f32_e32 v12, v12
	s_nop 0
	v_add_f32_e32 v12, 1.0, v12
	v_rcp_f32_e32 v12, v12
	s_nop 0
	v_mul_f32_e32 v12, v17, v12
	v_add_f32_e32 v17, v249, v22
	v_mul_f32_e32 v17, 0xbfb8aa3b, v17
	v_exp_f32_e32 v17, v17
	v_cvt_pk_bf16_f32 v12, v16, v12
	v_lshlrev_b32_e32 v16, 16, v208
	v_add_f32_e32 v17, 1.0, v17
	v_rcp_f32_e32 v17, v17
	s_nop 0
	v_mul_f32_e32 v17, v13, v17
	v_add_f32_e32 v13, v246, v29
	v_mul_f32_e32 v13, 0xbfb8aa3b, v13
	v_exp_f32_e32 v13, v13
	s_nop 0
	v_add_f32_e32 v13, 1.0, v13
	v_rcp_f32_e32 v13, v13
	s_nop 0
	v_mul_f32_e32 v13, v18, v13
	v_add_f32_e32 v18, v250, v31
	v_mul_f32_e32 v18, 0xbfb8aa3b, v18
	v_exp_f32_e32 v18, v18
	s_nop 0
	v_add_f32_e32 v18, 1.0, v18
	v_rcp_f32_e32 v18, v18
	s_nop 0
	v_mul_f32_e32 v18, v14, v18
	v_add_f32_e32 v14, v247, v21
	v_mul_f32_e32 v14, 0xbfb8aa3b, v14
	v_exp_f32_e32 v14, v14
	s_nop 0
	v_add_f32_e32 v14, 1.0, v14
	v_rcp_f32_e32 v14, v14
	s_nop 0
	v_mul_f32_e32 v14, v19, v14
	v_add_f32_e32 v19, v251, v23
	v_mul_f32_e32 v19, 0xbfb8aa3b, v19
	v_exp_f32_e32 v19, v19
	v_cvt_pk_bf16_f32 v13, v13, v14
	v_cvt_pk_bf16_f32 v14, v28, v17
	v_and_b32_e32 v17, 0xffff0000, v208
	v_add_f32_e32 v19, 1.0, v19
	v_rcp_f32_e32 v19, v19
	s_nop 0
	v_mul_f32_e32 v15, v15, v19
	v_cvt_pk_bf16_f32 v15, v18, v15
	global_store_dwordx4 v[78:79], v[12:15], off offset:256
	v_lshlrev_b32_e32 v18, 16, v209
	v_and_b32_e32 v19, 0xffff0000, v209
	v_lshlrev_b32_e32 v12, 16, v206
	v_add_f32_e32 v12, v244, v12
	v_mul_f32_e32 v12, 0xbfb8aa3b, v12
	v_exp_f32_e32 v12, v12
	v_and_b32_e32 v13, 0xffff0000, v206
	v_lshlrev_b32_e32 v14, 16, v207
	v_and_b32_e32 v15, 0xffff0000, v207
	v_add_f32_e32 v12, 1.0, v12
	v_rcp_f32_e32 v12, v12
	s_nop 0
	v_mul_f32_e32 v8, v8, v12
	v_add_f32_e32 v12, v248, v16
	v_mul_f32_e32 v12, 0xbfb8aa3b, v12
	v_exp_f32_e32 v12, v12
	s_nop 0
	v_add_f32_e32 v12, 1.0, v12
	v_rcp_f32_e32 v12, v12
	s_nop 0
	v_mul_f32_e32 v12, v4, v12
	v_add_f32_e32 v4, v245, v13
	v_mul_f32_e32 v4, 0xbfb8aa3b, v4
	v_exp_f32_e32 v4, v4
	s_nop 0
	v_add_f32_e32 v4, 1.0, v4
	v_rcp_f32_e32 v4, v4
	s_nop 0
	v_mul_f32_e32 v4, v9, v4
	v_add_f32_e32 v9, v249, v17
	v_mul_f32_e32 v9, 0xbfb8aa3b, v9
	v_exp_f32_e32 v9, v9
	v_cvt_pk_bf16_f32 v4, v8, v4
	s_nop 0
	v_add_f32_e32 v9, 1.0, v9
	v_rcp_f32_e32 v9, v9
	s_nop 0
	v_mul_f32_e32 v9, v5, v9
	v_add_f32_e32 v5, v246, v14
	v_mul_f32_e32 v5, 0xbfb8aa3b, v5
	v_exp_f32_e32 v5, v5
	s_nop 0
	v_add_f32_e32 v5, 1.0, v5
	v_rcp_f32_e32 v5, v5
	s_nop 0
	v_mul_f32_e32 v5, v10, v5
	v_add_f32_e32 v10, v250, v18
	v_mul_f32_e32 v10, 0xbfb8aa3b, v10
	v_exp_f32_e32 v10, v10
	s_nop 0
	v_add_f32_e32 v10, 1.0, v10
	v_rcp_f32_e32 v10, v10
	s_nop 0
	v_mul_f32_e32 v10, v6, v10
	v_add_f32_e32 v6, v247, v15
	v_mul_f32_e32 v6, 0xbfb8aa3b, v6
	v_exp_f32_e32 v6, v6
	s_nop 0
	v_add_f32_e32 v6, 1.0, v6
	v_rcp_f32_e32 v6, v6
	s_nop 0
	v_mul_f32_e32 v6, v11, v6
	v_add_f32_e32 v11, v251, v19
	v_mul_f32_e32 v11, 0xbfb8aa3b, v11
	v_exp_f32_e32 v11, v11
	v_cvt_pk_bf16_f32 v5, v5, v6
	v_cvt_pk_bf16_f32 v6, v12, v9
	s_nop 0
	v_add_f32_e32 v11, 1.0, v11
	v_rcp_f32_e32 v11, v11
	s_nop 0
	v_mul_f32_e32 v7, v7, v11
	v_cvt_pk_bf16_f32 v7, v10, v7
	global_store_dwordx4 v[76:77], v[4:7], off offset:256
	s_cbranch_vccnz .LBB0_399
	s_andn2_b64 vcc, exec, s[36:37]
	s_cbranch_vccnz .LBB0_398
	s_barrier
	s_branch .LBB0_398

; #define GAS __attribute__((address_space(1)))
; __device__ __forceinline__ void unpack8(const v4u v, float (&f)[8]) { f[0] = bflo(v.x); f[1] = bfhi(v.x); f[2] = bflo(v.y); f[3] = bfhi(v.y); f[4] = bflo(v.z); f[5] = bfhi(v.z); f[6] = bflo(v.w); f[7] = bfhi(v.w); }
; __device__ __forceinline__ v4u pack8(const float (&f)[8]) { v4u o; o.x = cvt_pk_bf16(f[0], f[1]); o.y = cvt_pk_bf16(f[2], f[3]); o.z = cvt_pk_bf16(f[4], f[5]); o.w = cvt_pk_bf16(f[6], f[7]); return o; }
; __device__ __forceinline__ float sigmoidf_(float x) { return __builtin_amdgcn_rcpf(1.f + __expf(-x)); }
;     __device__ __forceinline__ void operator()(const f32x4 (&acc)[2][2][4][2], const pg8::Unit& u, int wr, int wc, int fr, int fq) const {
;         const int row0 = u.pm * 256 + wr * 64 + fr, col0 = u.pn * 256 + wc * 32 + 8 * fq;
; #pragma unroll
;         for (int bj = 0; bj < 2; ++bj) { const int col = col0 + bj * 128;
;             const f32x4 b0 = *(const GAS f32x4*)(bgate + WHICH * DM + col), b1 = *(const GAS f32x4*)(bgate + WHICH * DM + col + 4);
; #pragma unroll
;             for (int aim = 0; aim < 4; ++aim) { const int ai = aim >> 1, mb = (aim & 1) * 2;
;                 v4u gv[4], tv[4];
; #pragma unroll
;                 for (int m = mb; m < mb + 2; ++m) { const int row = row0 + ai * 128 + m * 16;
;                     gv[m] = __builtin_nontemporal_load((const GAS v4u*)(proj + (size_t)row * NPROJ + OFF_GATE + WHICH * DM + col));
;                     if (WHICH == 1) tv[m] = *(const GAS v4u*)(ta + (size_t)row * DM + col); }
; #pragma unroll
;                 for (int m = mb; m < mb + 2; ++m) { const int row = row0 + ai * 128 + m * 16; float g[8]; unpack8(gv[m], g);
;                     const f32x4 a0 = acc[ai][bj][m][0], a1 = acc[ai][bj][m][1]; float r[8];
; #pragma unroll
;                     for (int e = 0; e < 4; ++e) { r[e] = sigmoidf_(g[e] + b0[e]) * a0[e]; r[4 + e] = sigmoidf_(g[4 + e] + b1[e]) * a1[e]; }
;                     if (WHICH == 0) *(GAS v4u*)(ta + (size_t)row * DM + col) = pack8(r);
;                     else { float tf[8]; unpack8(tv[m], tf);
; #pragma unroll
;                         for (int e = 0; e < 8; ++e) r[e] += tf[e];
;                         *(GAS v4u*)(mix + (size_t)row * DM + col) = pack8(r); } }
.LBB0_488:
	v_lshl_add_u32 v170, s22, 8, v179
	v_lshl_or_b32 v158, s9, 8, v189
	v_mov_b64_e32 v[186:187], s[42:43]
	v_ashrrev_i32_e32 v159, 31, v158
	v_readlane_b32 s14, v253, 51
	v_mad_i64_i32 v[140:141], s[0:1], v170, s4, v[186:187]
	s_mov_b64 s[16:17], 0x9000
	v_readlane_b32 s15, v253, 52
	v_lshlrev_b64 v[168:169], 1, v[158:159]
	v_lshl_add_u64 v[162:163], v[140:141], 0, s[16:17]
	v_lshl_add_u64 v[104:105], v[158:159], 2, s[14:15]
	v_lshl_add_u64 v[140:141], v[162:163], 0, v[168:169]
	global_load_dwordx4 v[100:103], v[104:105], off offset:16
	s_nop 0
	global_load_dwordx4 v[104:107], v[104:105], off
	v_ashrrev_i32_e32 v171, 31, v170
	global_load_dwordx4 v[192:195], v[140:141], off nt
	v_lshl_add_u64 v[184:185], s[44:45], 0, v[168:169]
	v_lshlrev_b64 v[160:161], 12, v[170:171]
	v_lshl_add_u64 v[140:141], v[184:185], 0, v[160:161]
	global_load_dwordx4 v[196:199], v[140:141], off
	v_or_b32_e32 v140, 16, v170
	v_mad_i64_i32 v[142:143], s[0:1], v140, s4, v[186:187]
	v_lshl_add_u64 v[164:165], v[142:143], 0, s[16:17]
	v_lshl_add_u64 v[142:143], v[164:165], 0, v[168:169]
	global_load_dwordx4 v[144:147], v[142:143], off nt
	v_ashrrev_i32_e32 v141, 31, v140
	v_lshlrev_b64 v[166:167], 12, v[140:141]
	v_lshl_add_u64 v[140:141], v[184:185], 0, v[166:167]
	global_load_dwordx4 v[140:143], v[140:141], off
	s_nop 1
	v_or_b32_e32 v251, 32, v170
	v_mad_i64_i32 v[248:249], s[60:61], v251, s4, v[186:187]
	v_lshl_add_u64 v[246:247], v[248:249], 0, s[16:17]
	v_lshl_add_u64 v[244:245], v[246:247], 0, v[168:169]
	global_load_dwordx4 v[234:237], v[244:245], off nt
	v_or_b32_e32 v251, 32, v170
	v_ashrrev_i32_e32 v250, 31, v251
	v_mov_b32_e32 v246, v251
	v_mov_b32_e32 v247, v250
	v_lshlrev_b64 v[248:249], 12, v[246:247]
	v_lshl_add_u64 v[244:245], v[184:185], 0, v[248:249]
	global_load_dwordx4 v[230:233], v[244:245], off
	v_or_b32_e32 v251, 48, v170
	v_mad_i64_i32 v[248:249], s[60:61], v251, s4, v[186:187]
	v_lshl_add_u64 v[246:247], v[248:249], 0, s[16:17]
	v_lshl_add_u64 v[244:245], v[246:247], 0, v[168:169]
	global_load_dwordx4 v[226:229], v[244:245], off nt
	v_or_b32_e32 v251, 48, v170
	v_ashrrev_i32_e32 v250, 31, v251
	v_mov_b32_e32 v246, v251
	v_mov_b32_e32 v247, v250
	v_lshlrev_b64 v[248:249], 12, v[246:247]
	v_lshl_add_u64 v[244:245], v[184:185], 0, v[248:249]
	global_load_dwordx4 v[222:225], v[244:245], off
	v_add_u32_e32 v251, 0x80, v170
	v_mad_i64_i32 v[248:249], s[60:61], v251, s4, v[186:187]
	v_lshl_add_u64 v[246:247], v[248:249], 0, s[16:17]
	v_lshl_add_u64 v[244:245], v[246:247], 0, v[168:169]
	global_load_dwordx4 v[218:221], v[244:245], off nt
	v_add_u32_e32 v251, 0x80, v170
	v_ashrrev_i32_e32 v250, 31, v251
	v_mov_b32_e32 v246, v251
	v_mov_b32_e32 v247, v250
	v_lshlrev_b64 v[248:249], 12, v[246:247]
	v_lshl_add_u64 v[244:245], v[184:185], 0, v[248:249]
	global_load_dwordx4 v[214:217], v[244:245], off
	v_add_u32_e32 v251, 0x90, v170
	v_mad_i64_i32 v[248:249], s[60:61], v251, s4, v[186:187]
	v_lshl_add_u64 v[246:247], v[248:249], 0, s[16:17]
	v_lshl_add_u64 v[244:245], v[246:247], 0, v[168:169]
	global_load_dwordx4 v[210:213], v[244:245], off nt
	v_add_u32_e32 v251, 0x90, v170
	v_ashrrev_i32_e32 v250, 31, v251
	v_mov_b32_e32 v246, v251
	v_mov_b32_e32 v247, v250
	v_lshlrev_b64 v[248:249], 12, v[246:247]
	v_lshl_add_u64 v[244:245], v[184:185], 0, v[248:249]
	global_load_dwordx4 v[206:209], v[244:245], off
	s_andn2_b64 vcc, exec, s[40:41]
	s_waitcnt vmcnt(8)
	v_lshlrev_b32_e32 v159, 16, v192
	v_and_b32_e32 v171, 0xffff0000, v192
	v_lshlrev_b32_e32 v191, 16, v193
	v_and_b32_e32 v192, 0xffff0000, v193
	v_lshlrev_b32_e32 v193, 16, v194
	v_and_b32_e32 v194, 0xffff0000, v194
	v_add_f32_e32 v159, v104, v159
	v_add_f32_e32 v171, v105, v171
	v_lshlrev_b32_e32 v200, 16, v195
	v_and_b32_e32 v195, 0xffff0000, v195
	v_mul_f32_e32 v159, 0xbfb8aa3b, v159
	v_add_f32_e32 v193, v100, v193
	v_mul_f32_e32 v171, 0xbfb8aa3b, v171
	v_add_f32_e32 v194, v101, v194
	v_add_f32_e32 v191, v106, v191
	v_add_f32_e32 v192, v107, v192
	v_exp_f32_e32 v159, v159
	v_mul_f32_e32 v193, 0xbfb8aa3b, v193
	v_exp_f32_e32 v171, v171
	v_mul_f32_e32 v194, 0xbfb8aa3b, v194
	v_mul_f32_e32 v191, 0xbfb8aa3b, v191
	v_add_f32_e32 v200, v102, v200
	v_mul_f32_e32 v192, 0xbfb8aa3b, v192
	v_add_f32_e32 v195, v103, v195
	v_exp_f32_e32 v193, v193
	v_exp_f32_e32 v194, v194
	v_exp_f32_e32 v191, v191
	v_mul_f32_e32 v200, 0xbfb8aa3b, v200
	v_exp_f32_e32 v192, v192
	v_mul_f32_e32 v195, 0xbfb8aa3b, v195
	v_exp_f32_e32 v200, v200
	v_exp_f32_e32 v195, v195
	v_add_f32_e32 v159, 1.0, v159
	v_add_f32_e32 v171, 1.0, v171
	v_rcp_f32_e32 v159, v159
	v_add_f32_e32 v193, 1.0, v193
	v_rcp_f32_e32 v171, v171
	v_add_f32_e32 v194, 1.0, v194
	v_add_f32_e32 v191, 1.0, v191
	v_add_f32_e32 v192, 1.0, v192
	v_rcp_f32_e32 v193, v193
	v_rcp_f32_e32 v194, v194
	v_rcp_f32_e32 v191, v191
	v_add_f32_e32 v200, 1.0, v200
	v_rcp_f32_e32 v192, v192
	v_add_f32_e32 v195, 1.0, v195
	v_rcp_f32_e32 v200, v200
	v_rcp_f32_e32 v195, v195
	v_lshlrev_b32_e32 v201, 16, v196
	v_and_b32_e32 v196, 0xffff0000, v196
	v_lshlrev_b32_e32 v202, 16, v197
	v_and_b32_e32 v197, 0xffff0000, v197
	v_lshlrev_b32_e32 v203, 16, v198
	v_and_b32_e32 v198, 0xffff0000, v198
	v_fmac_f32_e32 v201, v136, v159
	v_fmac_f32_e32 v196, v137, v171
	v_lshl_add_u64 v[136:137], s[46:47], 0, v[160:161]
	v_lshlrev_b32_e32 v204, 16, v199
	v_and_b32_e32 v199, 0xffff0000, v199
	v_fmac_f32_e32 v202, v138, v191
	v_fmac_f32_e32 v197, v139, v192
	v_fmac_f32_e32 v203, v132, v193
	v_fmac_f32_e32 v198, v133, v194
	v_cvt_pk_bf16_f32 v132, v201, v196
	v_cvt_pk_bf16_f32 v133, v202, v197
	v_lshl_add_u64 v[136:137], v[136:137], 0, v[168:169]
	v_fmac_f32_e32 v204, v134, v200
	v_fmac_f32_e32 v199, v135, v195
; #define GAS __attribute__((address_space(1)))
; __device__ __forceinline__ void unpack8(const v4u v, float (&f)[8]) { f[0] = bflo(v.x); f[1] = bfhi(v.x); f[2] = bflo(v.y); f[3] = bfhi(v.y); f[4] = bflo(v.z); f[5] = bfhi(v.z); f[6] = bflo(v.w); f[7] = bfhi(v.w); }
; __device__ __forceinline__ v4u pack8(const float (&f)[8]) { v4u o; o.x = cvt_pk_bf16(f[0], f[1]); o.y = cvt_pk_bf16(f[2], f[3]); o.z = cvt_pk_bf16(f[4], f[5]); o.w = cvt_pk_bf16(f[6], f[7]); return o; }
; __device__ __forceinline__ float sigmoidf_(float x) { return __builtin_amdgcn_rcpf(1.f + __expf(-x)); }
;     __device__ __forceinline__ void operator()(const f32x4 (&acc)[2][2][4][2], const pg8::Unit& u, int wr, int wc, int fr, int fq) const {
;     ...
;         for (int bj = 0; bj < 2; ++bj) { const int col = col0 + bj * 128;
;             const f32x4 b0 = *(const GAS f32x4*)(bgate + WHICH * DM + col), b1 = *(const GAS f32x4*)(bgate + WHICH * DM + col + 4);
; #pragma unroll
;             for (int aim = 0; aim < 4; ++aim) { const int ai = aim >> 1, mb = (aim & 1) * 2;
;                 v4u gv[4], tv[4];
; #pragma unroll
;                 for (int m = mb; m < mb + 2; ++m) { const int row = row0 + ai * 128 + m * 16;
;                     gv[m] = __builtin_nontemporal_load((const GAS v4u*)(proj + (size_t)row * NPROJ + OFF_GATE + WHICH * DM + col));
;                     if (WHICH == 1) tv[m] = *(const GAS v4u*)(ta + (size_t)row * DM + col); }
; #pragma unroll
;                 for (int m = mb; m < mb + 2; ++m) { const int row = row0 + ai * 128 + m * 16; float g[8]; unpack8(gv[m], g);
;                     const f32x4 a0 = acc[ai][bj][m][0], a1 = acc[ai][bj][m][1]; float r[8];
; #pragma unroll
;                     for (int e = 0; e < 4; ++e) { r[e] = sigmoidf_(g[e] + b0[e]) * a0[e]; r[4 + e] = sigmoidf_(g[4 + e] + b1[e]) * a1[e]; }
;                     if (WHICH == 0) *(GAS v4u*)(ta + (size_t)row * DM + col) = pack8(r);
;                     else { float tf[8]; unpack8(tv[m], tf);
; #pragma unroll
;                         for (int e = 0; e < 8; ++e) r[e] += tf[e];
;                         *(GAS v4u*)(mix + (size_t)row * DM + col) = pack8(r); } }
	v_cvt_pk_bf16_f32 v134, v203, v198
	v_cvt_pk_bf16_f32 v135, v204, v199
	global_store_dwordx4 v[136:137], v[132:135], off
	v_add_u32_e32 v251, 0xa0, v170
	v_mad_i64_i32 v[248:249], s[60:61], v251, s4, v[186:187]
	v_lshl_add_u64 v[246:247], v[248:249], 0, s[16:17]
	v_lshl_add_u64 v[244:245], v[246:247], 0, v[168:169]
	global_load_dwordx4 v[202:205], v[244:245], off nt
	v_lshlrev_b32_e32 v138, 16, v146
	v_and_b32_e32 v139, 0xffff0000, v146
	v_lshlrev_b32_e32 v132, 16, v144
	v_and_b32_e32 v133, 0xffff0000, v144
	v_add_f32_e32 v132, v104, v132
	v_add_f32_e32 v133, v105, v133
	v_lshlrev_b32_e32 v134, 16, v145
	v_and_b32_e32 v135, 0xffff0000, v145
	v_lshlrev_b32_e32 v144, 16, v147
	v_and_b32_e32 v145, 0xffff0000, v147
	v_mul_f32_e32 v132, 0xbfb8aa3b, v132
	v_add_f32_e32 v138, v100, v138
	v_mul_f32_e32 v133, 0xbfb8aa3b, v133
	v_exp_f32_e32 v132, v132
	v_mul_f32_e32 v138, 0xbfb8aa3b, v138
	v_exp_f32_e32 v133, v133
	v_add_f32_e32 v139, v101, v139
	v_add_f32_e32 v134, v106, v134
	v_add_f32_e32 v144, v102, v144
	v_add_f32_e32 v135, v107, v135
	v_add_f32_e32 v145, v103, v145
	v_exp_f32_e32 v138, v138
	v_mul_f32_e32 v139, 0xbfb8aa3b, v139
	v_mul_f32_e32 v134, 0xbfb8aa3b, v134
	v_mul_f32_e32 v144, 0xbfb8aa3b, v144
	v_mul_f32_e32 v135, 0xbfb8aa3b, v135
	v_mul_f32_e32 v145, 0xbfb8aa3b, v145
	v_exp_f32_e32 v139, v139
	v_exp_f32_e32 v134, v134
	v_exp_f32_e32 v144, v144
	v_exp_f32_e32 v135, v135
	v_exp_f32_e32 v145, v145
	v_add_f32_e32 v132, 1.0, v132
	v_add_f32_e32 v133, 1.0, v133
	v_rcp_f32_e32 v132, v132
	v_add_f32_e32 v138, 1.0, v138
	v_rcp_f32_e32 v133, v133
	v_rcp_f32_e32 v138, v138
	v_add_f32_e32 v139, 1.0, v139
	v_add_f32_e32 v134, 1.0, v134
	v_add_f32_e32 v144, 1.0, v144
	v_add_f32_e32 v135, 1.0, v135
	v_add_f32_e32 v145, 1.0, v145
	v_rcp_f32_e32 v139, v139
	v_rcp_f32_e32 v134, v134
	v_rcp_f32_e32 v144, v144
	v_rcp_f32_e32 v135, v135
	v_rcp_f32_e32 v145, v145
	v_lshlrev_b32_e32 v146, 16, v140
	v_and_b32_e32 v140, 0xffff0000, v140
	v_lshlrev_b32_e32 v159, 16, v142
	v_fmac_f32_e32 v146, v128, v132
	v_fmac_f32_e32 v140, v129, v133
	v_lshl_add_u64 v[128:129], s[46:47], 0, v[166:167]
	v_lshlrev_b32_e32 v147, 16, v141
	v_and_b32_e32 v141, 0xffff0000, v141
	v_and_b32_e32 v142, 0xffff0000, v142
	v_lshlrev_b32_e32 v171, 16, v143
	v_and_b32_e32 v143, 0xffff0000, v143
	v_fmac_f32_e32 v159, v124, v138
	v_cvt_pk_bf16_f32 v124, v146, v140
	v_lshl_add_u64 v[128:129], v[128:129], 0, v[168:169]
	v_fmac_f32_e32 v147, v130, v134
	v_fmac_f32_e32 v141, v131, v135
	v_fmac_f32_e32 v142, v125, v139
	v_fmac_f32_e32 v171, v126, v144
	v_fmac_f32_e32 v143, v127, v145
	v_cvt_pk_bf16_f32 v125, v147, v141
	v_cvt_pk_bf16_f32 v126, v159, v142
	v_cvt_pk_bf16_f32 v127, v171, v143
	global_store_dwordx4 v[128:129], v[124:127], off
	s_nop 1
	v_or_b32_e32 v124, 32, v170
	v_mad_i64_i32 v[126:127], s[0:1], v124, s4, v[186:187]
	v_lshl_add_u64 v[130:131], v[126:127], 0, s[16:17]
	v_lshl_add_u64 v[126:127], v[130:131], 0, v[168:169]
	s_nop 0
	v_ashrrev_i32_e32 v125, 31, v124
	v_lshlrev_b64 v[132:133], 12, v[124:125]
	v_lshl_add_u64 v[124:125], v[184:185], 0, v[132:133]
	s_nop 0
	v_or_b32_e32 v124, 48, v170
	v_mad_i64_i32 v[126:127], s[0:1], v124, s4, v[186:187]
	v_lshl_add_u64 v[134:135], v[126:127], 0, s[16:17]
	v_lshl_add_u64 v[126:127], v[134:135], 0, v[168:169]
	s_nop 0
	v_ashrrev_i32_e32 v125, 31, v124
	v_lshlrev_b64 v[138:139], 12, v[124:125]
	v_lshl_add_u64 v[124:125], v[184:185], 0, v[138:139]
	s_nop 0
	s_waitcnt vmcnt(10)
	v_lshlrev_b32_e32 v191, 16, v236
	v_and_b32_e32 v142, 0xffff0000, v236
	v_lshlrev_b32_e32 v159, 16, v234
	v_and_b32_e32 v140, 0xffff0000, v234
	v_lshlrev_b32_e32 v171, 16, v235
	v_and_b32_e32 v141, 0xffff0000, v235
	v_lshlrev_b32_e32 v196, 16, v237
	v_and_b32_e32 v143, 0xffff0000, v237
	v_add_f32_e32 v191, v100, v191
	v_add_f32_e32 v142, v101, v142
	v_add_f32_e32 v159, v104, v159
	v_mul_f32_e32 v191, 0xbfb8aa3b, v191
	v_add_f32_e32 v140, v105, v140
	v_mul_f32_e32 v142, 0xbfb8aa3b, v142
	v_add_f32_e32 v171, v106, v171
	v_add_f32_e32 v196, v102, v196
	v_add_f32_e32 v141, v107, v141
	v_add_f32_e32 v143, v103, v143
	v_mul_f32_e32 v159, 0xbfb8aa3b, v159
	v_exp_f32_e32 v191, v191
	v_mul_f32_e32 v140, 0xbfb8aa3b, v140
	v_exp_f32_e32 v142, v142
	v_mul_f32_e32 v171, 0xbfb8aa3b, v171
	v_mul_f32_e32 v196, 0xbfb8aa3b, v196
	v_mul_f32_e32 v141, 0xbfb8aa3b, v141
	v_mul_f32_e32 v143, 0xbfb8aa3b, v143
	v_exp_f32_e32 v159, v159
	v_exp_f32_e32 v140, v140
	v_exp_f32_e32 v171, v171
	v_exp_f32_e32 v196, v196
	v_exp_f32_e32 v141, v141
	v_exp_f32_e32 v143, v143
	v_add_f32_e32 v191, 1.0, v191
	v_add_f32_e32 v142, 1.0, v142
	v_add_f32_e32 v159, 1.0, v159
	v_rcp_f32_e32 v191, v191
	v_add_f32_e32 v140, 1.0, v140
	v_rcp_f32_e32 v142, v142
	v_add_f32_e32 v171, 1.0, v171
	v_add_f32_e32 v196, 1.0, v196
	v_add_f32_e32 v141, 1.0, v141
	v_add_f32_e32 v143, 1.0, v143
	v_rcp_f32_e32 v159, v159
	v_rcp_f32_e32 v140, v140
	v_rcp_f32_e32 v171, v171
	v_rcp_f32_e32 v196, v196
	v_rcp_f32_e32 v141, v141
	v_rcp_f32_e32 v143, v143
	s_waitcnt vmcnt(9)
; #define GAS __attribute__((address_space(1)))
; __device__ __forceinline__ void unpack8(const v4u v, float (&f)[8]) { f[0] = bflo(v.x); f[1] = bfhi(v.x); f[2] = bflo(v.y); f[3] = bfhi(v.y); f[4] = bflo(v.z); f[5] = bfhi(v.z); f[6] = bflo(v.w); f[7] = bfhi(v.w); }
; __device__ __forceinline__ v4u pack8(const float (&f)[8]) { v4u o; o.x = cvt_pk_bf16(f[0], f[1]); o.y = cvt_pk_bf16(f[2], f[3]); o.z = cvt_pk_bf16(f[4], f[5]); o.w = cvt_pk_bf16(f[6], f[7]); return o; }
; __device__ __forceinline__ float sigmoidf_(float x) { return __builtin_amdgcn_rcpf(1.f + __expf(-x)); }
;     __device__ __forceinline__ void operator()(const f32x4 (&acc)[2][2][4][2], const pg8::Unit& u, int wr, int wc, int fr, int fq) const {
;     ...
;         for (int bj = 0; bj < 2; ++bj) { const int col = col0 + bj * 128;
;             const f32x4 b0 = *(const GAS f32x4*)(bgate + WHICH * DM + col), b1 = *(const GAS f32x4*)(bgate + WHICH * DM + col + 4);
; #pragma unroll
;             for (int aim = 0; aim < 4; ++aim) { const int ai = aim >> 1, mb = (aim & 1) * 2;
;                 v4u gv[4], tv[4];
; #pragma unroll
;                 for (int m = mb; m < mb + 2; ++m) { const int row = row0 + ai * 128 + m * 16;
;                     gv[m] = __builtin_nontemporal_load((const GAS v4u*)(proj + (size_t)row * NPROJ + OFF_GATE + WHICH * DM + col));
;                     if (WHICH == 1) tv[m] = *(const GAS v4u*)(ta + (size_t)row * DM + col); }
; #pragma unroll
;                 for (int m = mb; m < mb + 2; ++m) { const int row = row0 + ai * 128 + m * 16; float g[8]; unpack8(gv[m], g);
;                     const f32x4 a0 = acc[ai][bj][m][0], a1 = acc[ai][bj][m][1]; float r[8];
; #pragma unroll
;                     for (int e = 0; e < 4; ++e) { r[e] = sigmoidf_(g[e] + b0[e]) * a0[e]; r[4 + e] = sigmoidf_(g[4 + e] + b1[e]) * a1[e]; }
;                     if (WHICH == 0) *(GAS v4u*)(ta + (size_t)row * DM + col) = pack8(r);
;                     else { float tf[8]; unpack8(tv[m], tf);
; #pragma unroll
;                         for (int e = 0; e < 8; ++e) r[e] += tf[e];
;                         *(GAS v4u*)(mix + (size_t)row * DM + col) = pack8(r); } }
	v_lshlrev_b32_e32 v199, 16, v232
	v_and_b32_e32 v146, 0xffff0000, v232
	v_lshlrev_b32_e32 v197, 16, v230
	v_and_b32_e32 v144, 0xffff0000, v230
	v_lshlrev_b32_e32 v198, 16, v231
	v_and_b32_e32 v145, 0xffff0000, v231
	v_lshlrev_b32_e32 v200, 16, v233
	v_and_b32_e32 v147, 0xffff0000, v233
	v_fmac_f32_e32 v199, v116, v191
	v_fmac_f32_e32 v146, v117, v142
	v_lshl_add_u64 v[116:117], s[46:47], 0, v[132:133]
	v_fmac_f32_e32 v197, v120, v159
	v_fmac_f32_e32 v144, v121, v140
	v_fmac_f32_e32 v198, v122, v171
	v_fmac_f32_e32 v145, v123, v141
	v_fmac_f32_e32 v200, v118, v196
	v_fmac_f32_e32 v147, v119, v143
	v_cvt_pk_bf16_f32 v118, v197, v144
	v_cvt_pk_bf16_f32 v119, v198, v145
	v_lshl_add_u64 v[116:117], v[116:117], 0, v[168:169]
	v_cvt_pk_bf16_f32 v120, v199, v146
	v_cvt_pk_bf16_f32 v121, v200, v147
	global_store_dwordx4 v[116:117], v[118:121], off
	v_add_u32_e32 v251, 0xa0, v170
	v_ashrrev_i32_e32 v250, 31, v251
	v_mov_b32_e32 v246, v251
	v_mov_b32_e32 v247, v250
	v_lshlrev_b64 v[248:249], 12, v[246:247]
	v_lshl_add_u64 v[244:245], v[184:185], 0, v[248:249]
	global_load_dwordx4 v[234:237], v[244:245], off
	v_add_u32_e32 v251, 0xb0, v170
	v_mad_i64_i32 v[248:249], s[60:61], v251, s4, v[186:187]
	v_lshl_add_u64 v[246:247], v[248:249], 0, s[16:17]
	v_lshl_add_u64 v[244:245], v[246:247], 0, v[168:169]
	global_load_dwordx4 v[230:233], v[244:245], off nt
	v_add_u32_e32 v251, 0xb0, v170
	v_ashrrev_i32_e32 v250, 31, v251
	v_mov_b32_e32 v246, v251
	v_mov_b32_e32 v247, v250
	v_lshlrev_b64 v[248:249], 12, v[246:247]
	v_lshl_add_u64 v[244:245], v[184:185], 0, v[248:249]
	global_load_dwordx4 v[198:201], v[244:245], off
	s_waitcnt vmcnt(12)
	v_lshlrev_b32_e32 v122, 16, v228
	v_and_b32_e32 v123, 0xffff0000, v228
	v_lshlrev_b32_e32 v118, 16, v226
	v_and_b32_e32 v119, 0xffff0000, v226
	v_add_f32_e32 v118, v104, v118
	v_add_f32_e32 v119, v105, v119
	v_lshlrev_b32_e32 v120, 16, v227
	v_and_b32_e32 v121, 0xffff0000, v227
	v_lshlrev_b32_e32 v140, 16, v229
	v_and_b32_e32 v141, 0xffff0000, v229
	v_mul_f32_e32 v118, 0xbfb8aa3b, v118
	v_add_f32_e32 v122, v100, v122
	v_mul_f32_e32 v119, 0xbfb8aa3b, v119
	v_exp_f32_e32 v118, v118
	v_mul_f32_e32 v122, 0xbfb8aa3b, v122
	v_exp_f32_e32 v119, v119
	v_add_f32_e32 v123, v101, v123
	v_add_f32_e32 v120, v106, v120
	v_add_f32_e32 v140, v102, v140
	v_add_f32_e32 v121, v107, v121
	v_add_f32_e32 v141, v103, v141
	v_exp_f32_e32 v122, v122
	v_mul_f32_e32 v123, 0xbfb8aa3b, v123
	v_mul_f32_e32 v120, 0xbfb8aa3b, v120
	v_mul_f32_e32 v140, 0xbfb8aa3b, v140
	v_mul_f32_e32 v121, 0xbfb8aa3b, v121
	v_mul_f32_e32 v141, 0xbfb8aa3b, v141
	v_exp_f32_e32 v123, v123
	v_exp_f32_e32 v120, v120
	v_exp_f32_e32 v140, v140
	v_exp_f32_e32 v121, v121
	v_exp_f32_e32 v141, v141
	v_add_f32_e32 v118, 1.0, v118
	v_add_f32_e32 v119, 1.0, v119
	v_rcp_f32_e32 v118, v118
	v_add_f32_e32 v122, 1.0, v122
	v_rcp_f32_e32 v119, v119
	v_rcp_f32_e32 v122, v122
	v_add_f32_e32 v123, 1.0, v123
	v_add_f32_e32 v120, 1.0, v120
	v_add_f32_e32 v140, 1.0, v140
	v_add_f32_e32 v121, 1.0, v121
	v_add_f32_e32 v141, 1.0, v141
	v_rcp_f32_e32 v123, v123
	v_rcp_f32_e32 v120, v120
	v_rcp_f32_e32 v140, v140
	v_rcp_f32_e32 v121, v121
	v_rcp_f32_e32 v141, v141
	s_waitcnt vmcnt(11)
	v_lshlrev_b32_e32 v142, 16, v222
	v_and_b32_e32 v124, 0xffff0000, v222
	v_lshlrev_b32_e32 v144, 16, v224
	v_fmac_f32_e32 v142, v112, v118
	v_fmac_f32_e32 v124, v113, v119
	v_lshl_add_u64 v[112:113], s[46:47], 0, v[138:139]
	v_lshlrev_b32_e32 v143, 16, v223
	v_and_b32_e32 v125, 0xffff0000, v223
	v_and_b32_e32 v126, 0xffff0000, v224
	v_lshlrev_b32_e32 v145, 16, v225
	v_and_b32_e32 v127, 0xffff0000, v225
	v_fmac_f32_e32 v144, v108, v122
	v_cvt_pk_bf16_f32 v108, v142, v124
	v_lshl_add_u64 v[112:113], v[112:113], 0, v[168:169]
	v_fmac_f32_e32 v143, v114, v120
	v_fmac_f32_e32 v125, v115, v121
	v_fmac_f32_e32 v126, v109, v123
	v_fmac_f32_e32 v145, v110, v140
	v_fmac_f32_e32 v127, v111, v141
	v_cvt_pk_bf16_f32 v109, v143, v125
	v_cvt_pk_bf16_f32 v110, v144, v126
	v_cvt_pk_bf16_f32 v111, v145, v127
	global_store_dwordx4 v[112:113], v[108:111], off
	v_or_b32_e32 v251, 0x80, v158
	v_ashrrev_i32_e32 v250, 31, v251
	v_mov_b32_e32 v246, v251
	v_mov_b32_e32 v247, v250
	v_lshl_add_u64 v[248:249], v[246:247], 2, s[14:15]
	global_load_dwordx4 v[226:229], v[248:249], off offset:16
	v_or_b32_e32 v251, 0x80, v158
	v_ashrrev_i32_e32 v250, 31, v251
	v_mov_b32_e32 v246, v251
	v_mov_b32_e32 v247, v250
	v_lshl_add_u64 v[248:249], v[246:247], 2, s[14:15]
	global_load_dwordx4 v[222:225], v[248:249], off
	s_nop 1
	v_add_u32_e32 v108, 0x80, v170
	v_mad_i64_i32 v[110:111], s[0:1], v108, s4, v[186:187]
	v_lshl_add_u64 v[114:115], v[110:111], 0, s[16:17]
	v_lshl_add_u64 v[110:111], v[114:115], 0, v[168:169]
	s_nop 0
	v_ashrrev_i32_e32 v109, 31, v108
	v_lshlrev_b64 v[118:119], 12, v[108:109]
	v_lshl_add_u64 v[108:109], v[184:185], 0, v[118:119]
	s_nop 0
	v_add_u32_e32 v108, 0x90, v170
	v_mad_i64_i32 v[110:111], s[0:1], v108, s4, v[186:187]
	v_lshl_add_u64 v[120:121], v[110:111], 0, s[16:17]
	v_lshl_add_u64 v[110:111], v[120:121], 0, v[168:169]
	s_nop 0
	v_ashrrev_i32_e32 v109, 31, v108
	v_lshlrev_b64 v[122:123], 12, v[108:109]
	v_lshl_add_u64 v[108:109], v[184:185], 0, v[122:123]
	s_nop 0
	s_waitcnt vmcnt(13)
; #define GAS __attribute__((address_space(1)))
; __device__ __forceinline__ void unpack8(const v4u v, float (&f)[8]) { f[0] = bflo(v.x); f[1] = bfhi(v.x); f[2] = bflo(v.y); f[3] = bfhi(v.y); f[4] = bflo(v.z); f[5] = bfhi(v.z); f[6] = bflo(v.w); f[7] = bfhi(v.w); }
; __device__ __forceinline__ v4u pack8(const float (&f)[8]) { v4u o; o.x = cvt_pk_bf16(f[0], f[1]); o.y = cvt_pk_bf16(f[2], f[3]); o.z = cvt_pk_bf16(f[4], f[5]); o.w = cvt_pk_bf16(f[6], f[7]); return o; }
; __device__ __forceinline__ float sigmoidf_(float x) { return __builtin_amdgcn_rcpf(1.f + __expf(-x)); }
;     __device__ __forceinline__ void operator()(const f32x4 (&acc)[2][2][4][2], const pg8::Unit& u, int wr, int wc, int fr, int fq) const {
;     ...
;         for (int bj = 0; bj < 2; ++bj) { const int col = col0 + bj * 128;
;             const f32x4 b0 = *(const GAS f32x4*)(bgate + WHICH * DM + col), b1 = *(const GAS f32x4*)(bgate + WHICH * DM + col + 4);
; #pragma unroll
;             for (int aim = 0; aim < 4; ++aim) { const int ai = aim >> 1, mb = (aim & 1) * 2;
;                 v4u gv[4], tv[4];
; #pragma unroll
;                 for (int m = mb; m < mb + 2; ++m) { const int row = row0 + ai * 128 + m * 16;
;                     gv[m] = __builtin_nontemporal_load((const GAS v4u*)(proj + (size_t)row * NPROJ + OFF_GATE + WHICH * DM + col));
;                     if (WHICH == 1) tv[m] = *(const GAS v4u*)(ta + (size_t)row * DM + col); }
; #pragma unroll
;                 for (int m = mb; m < mb + 2; ++m) { const int row = row0 + ai * 128 + m * 16; float g[8]; unpack8(gv[m], g);
;                     const f32x4 a0 = acc[ai][bj][m][0], a1 = acc[ai][bj][m][1]; float r[8];
; #pragma unroll
;                     for (int e = 0; e < 4; ++e) { r[e] = sigmoidf_(g[e] + b0[e]) * a0[e]; r[4 + e] = sigmoidf_(g[4 + e] + b1[e]) * a1[e]; }
;                     if (WHICH == 0) *(GAS v4u*)(ta + (size_t)row * DM + col) = pack8(r);
;                     else { float tf[8]; unpack8(tv[m], tf);
; #pragma unroll
;                         for (int e = 0; e < 8; ++e) r[e] += tf[e];
;                         *(GAS v4u*)(mix + (size_t)row * DM + col) = pack8(r); } }
	v_lshlrev_b32_e32 v191, 16, v220
	v_and_b32_e32 v126, 0xffff0000, v220
	v_lshlrev_b32_e32 v159, 16, v218
	v_and_b32_e32 v124, 0xffff0000, v218
	v_lshlrev_b32_e32 v171, 16, v219
	v_and_b32_e32 v125, 0xffff0000, v219
	v_lshlrev_b32_e32 v192, 16, v221
	v_and_b32_e32 v127, 0xffff0000, v221
	v_add_f32_e32 v191, v100, v191
	v_add_f32_e32 v126, v101, v126
	v_add_f32_e32 v159, v104, v159
	v_mul_f32_e32 v191, 0xbfb8aa3b, v191
	v_add_f32_e32 v124, v105, v124
	v_mul_f32_e32 v126, 0xbfb8aa3b, v126
	v_add_f32_e32 v171, v106, v171
	v_add_f32_e32 v192, v102, v192
	v_add_f32_e32 v125, v107, v125
	v_add_f32_e32 v127, v103, v127
	v_mul_f32_e32 v159, 0xbfb8aa3b, v159
	v_exp_f32_e32 v191, v191
	v_mul_f32_e32 v124, 0xbfb8aa3b, v124
	v_exp_f32_e32 v126, v126
	v_mul_f32_e32 v171, 0xbfb8aa3b, v171
	v_mul_f32_e32 v192, 0xbfb8aa3b, v192
	v_mul_f32_e32 v125, 0xbfb8aa3b, v125
	v_mul_f32_e32 v127, 0xbfb8aa3b, v127
	v_exp_f32_e32 v159, v159
	v_exp_f32_e32 v124, v124
	v_exp_f32_e32 v171, v171
	v_exp_f32_e32 v192, v192
	v_exp_f32_e32 v125, v125
	v_exp_f32_e32 v127, v127
	v_add_f32_e32 v191, 1.0, v191
	v_add_f32_e32 v126, 1.0, v126
	v_add_f32_e32 v159, 1.0, v159
	v_rcp_f32_e32 v191, v191
	v_add_f32_e32 v124, 1.0, v124
	v_rcp_f32_e32 v126, v126
	v_add_f32_e32 v171, 1.0, v171
	v_add_f32_e32 v192, 1.0, v192
	v_add_f32_e32 v125, 1.0, v125
	v_add_f32_e32 v127, 1.0, v127
	v_rcp_f32_e32 v159, v159
	v_rcp_f32_e32 v124, v124
	v_rcp_f32_e32 v171, v171
	v_rcp_f32_e32 v192, v192
	v_rcp_f32_e32 v125, v125
	v_rcp_f32_e32 v127, v127
	s_waitcnt vmcnt(12)
	v_lshlrev_b32_e32 v195, 16, v216
	v_and_b32_e32 v142, 0xffff0000, v216
	v_lshlrev_b32_e32 v193, 16, v214
	v_and_b32_e32 v140, 0xffff0000, v214
	v_lshlrev_b32_e32 v194, 16, v215
	v_and_b32_e32 v141, 0xffff0000, v215
	v_lshlrev_b32_e32 v196, 16, v217
	v_and_b32_e32 v143, 0xffff0000, v217
	v_fmac_f32_e32 v195, v92, v191
	v_fmac_f32_e32 v142, v93, v126
	v_lshl_add_u64 v[92:93], s[46:47], 0, v[118:119]
	v_fmac_f32_e32 v193, v96, v159
	v_fmac_f32_e32 v140, v97, v124
	v_fmac_f32_e32 v194, v98, v171
	v_fmac_f32_e32 v141, v99, v125
	v_fmac_f32_e32 v196, v94, v192
	v_fmac_f32_e32 v143, v95, v127
	v_cvt_pk_bf16_f32 v94, v193, v140
	v_cvt_pk_bf16_f32 v95, v194, v141
	v_lshl_add_u64 v[92:93], v[92:93], 0, v[168:169]
	v_cvt_pk_bf16_f32 v96, v195, v142
	v_cvt_pk_bf16_f32 v97, v196, v143
	global_store_dwordx4 v[92:93], v[94:97], off
	v_or_b32_e32 v251, 0x80, v158
	v_ashrrev_i32_e32 v250, 31, v251
	v_mov_b32_e32 v246, v251
	v_mov_b32_e32 v247, v250
	v_lshlrev_b64 v[248:249], 1, v[246:247]
	v_lshl_add_u64 v[244:245], v[162:163], 0, v[248:249]
	global_load_dwordx4 v[218:221], v[244:245], off nt
	v_or_b32_e32 v251, 0x80, v158
	v_ashrrev_i32_e32 v250, 31, v251
	v_mov_b32_e32 v246, v251
	v_mov_b32_e32 v247, v250
	v_lshlrev_b64 v[248:249], 1, v[246:247]
	v_lshl_add_u64 v[244:245], s[44:45], 0, v[160:161]
	v_lshl_add_u64 v[216:217], v[244:245], 0, v[248:249]
	global_load_dwordx4 v[194:197], v[216:217], off
	v_or_b32_e32 v251, 0x80, v158
	v_ashrrev_i32_e32 v250, 31, v251
	v_mov_b32_e32 v246, v251
	v_mov_b32_e32 v247, v250
	v_lshlrev_b64 v[248:249], 1, v[246:247]
	v_lshl_add_u64 v[244:245], v[164:165], 0, v[248:249]
	global_load_dwordx4 v[214:217], v[244:245], off nt
	s_waitcnt vmcnt(15)
	v_lshlrev_b32_e32 v98, 16, v212
	v_and_b32_e32 v99, 0xffff0000, v212
	v_lshlrev_b32_e32 v94, 16, v210
	v_and_b32_e32 v95, 0xffff0000, v210
	v_add_f32_e32 v94, v104, v94
	v_add_f32_e32 v95, v105, v95
	v_lshlrev_b32_e32 v96, 16, v211
	v_and_b32_e32 v97, 0xffff0000, v211
	v_lshlrev_b32_e32 v124, 16, v213
	v_and_b32_e32 v125, 0xffff0000, v213
	v_mul_f32_e32 v94, 0xbfb8aa3b, v94
	v_add_f32_e32 v98, v100, v98
	v_mul_f32_e32 v95, 0xbfb8aa3b, v95
	v_exp_f32_e32 v94, v94
	v_mul_f32_e32 v98, 0xbfb8aa3b, v98
	v_exp_f32_e32 v95, v95
	v_add_f32_e32 v99, v101, v99
	v_add_f32_e32 v96, v106, v96
	v_add_f32_e32 v124, v102, v124
	v_add_f32_e32 v97, v107, v97
	v_add_f32_e32 v125, v103, v125
	v_exp_f32_e32 v98, v98
	v_mul_f32_e32 v99, 0xbfb8aa3b, v99
	v_mul_f32_e32 v96, 0xbfb8aa3b, v96
	v_mul_f32_e32 v124, 0xbfb8aa3b, v124
	v_mul_f32_e32 v97, 0xbfb8aa3b, v97
	v_mul_f32_e32 v125, 0xbfb8aa3b, v125
	v_exp_f32_e32 v99, v99
	v_exp_f32_e32 v96, v96
	v_exp_f32_e32 v124, v124
	v_exp_f32_e32 v97, v97
	v_exp_f32_e32 v125, v125
	v_add_f32_e32 v94, 1.0, v94
	v_add_f32_e32 v95, 1.0, v95
	v_rcp_f32_e32 v94, v94
	v_add_f32_e32 v98, 1.0, v98
	v_rcp_f32_e32 v95, v95
	v_rcp_f32_e32 v98, v98
	v_add_f32_e32 v99, 1.0, v99
	v_add_f32_e32 v96, 1.0, v96
	v_add_f32_e32 v124, 1.0, v124
	v_add_f32_e32 v97, 1.0, v97
	v_add_f32_e32 v125, 1.0, v125
	v_rcp_f32_e32 v99, v99
	v_rcp_f32_e32 v96, v96
	v_rcp_f32_e32 v124, v124
	v_rcp_f32_e32 v97, v97
	v_rcp_f32_e32 v125, v125
	s_waitcnt vmcnt(14)
	v_lshlrev_b32_e32 v126, 16, v206
	v_and_b32_e32 v108, 0xffff0000, v206
	v_lshlrev_b32_e32 v140, 16, v208
	v_fmac_f32_e32 v126, v88, v94
	v_fmac_f32_e32 v108, v89, v95
	v_lshl_add_u64 v[88:89], s[46:47], 0, v[122:123]
	v_lshlrev_b32_e32 v127, 16, v207
	v_and_b32_e32 v109, 0xffff0000, v207
	v_and_b32_e32 v110, 0xffff0000, v208
	v_lshlrev_b32_e32 v141, 16, v209
	v_and_b32_e32 v111, 0xffff0000, v209
	v_fmac_f32_e32 v140, v84, v98
	v_cvt_pk_bf16_f32 v84, v126, v108
	v_lshl_add_u64 v[88:89], v[88:89], 0, v[168:169]
	v_fmac_f32_e32 v127, v90, v96
	v_fmac_f32_e32 v109, v91, v97
	v_fmac_f32_e32 v110, v85, v99
	v_fmac_f32_e32 v141, v86, v124
	v_fmac_f32_e32 v111, v87, v125
	v_cvt_pk_bf16_f32 v85, v127, v109
	v_cvt_pk_bf16_f32 v86, v140, v110
	v_cvt_pk_bf16_f32 v87, v141, v111
	global_store_dwordx4 v[88:89], v[84:87], off
	v_or_b32_e32 v251, 0x80, v158
	v_ashrrev_i32_e32 v250, 31, v251
	v_mov_b32_e32 v246, v251
	v_mov_b32_e32 v247, v250
	v_lshlrev_b64 v[248:249], 1, v[246:247]
	v_lshl_add_u64 v[244:245], s[44:45], 0, v[166:167]
	v_lshl_add_u64 v[212:213], v[244:245], 0, v[248:249]
	global_load_dwordx4 v[208:211], v[212:213], off
	s_nop 1
	v_add_u32_e32 v84, 0xa0, v170
	v_mad_i64_i32 v[86:87], s[0:1], v84, s4, v[186:187]
	v_lshl_add_u64 v[90:91], v[86:87], 0, s[16:17]
	v_lshl_add_u64 v[86:87], v[90:91], 0, v[168:169]
	s_nop 0
	v_ashrrev_i32_e32 v85, 31, v84
	v_lshlrev_b64 v[94:95], 12, v[84:85]
	v_lshl_add_u64 v[84:85], v[184:185], 0, v[94:95]
	s_nop 0
	v_add_u32_e32 v84, 0xb0, v170
	v_mad_i64_i32 v[86:87], s[0:1], v84, s4, v[186:187]
	v_lshl_add_u64 v[96:97], v[86:87], 0, s[16:17]
	v_lshl_add_u64 v[86:87], v[96:97], 0, v[168:169]
	s_nop 0
	v_ashrrev_i32_e32 v85, 31, v84
	v_lshlrev_b64 v[98:99], 12, v[84:85]
	v_lshl_add_u64 v[84:85], v[184:185], 0, v[98:99]
	s_nop 0
	s_mov_b64 s[0:1], -1
	s_waitcnt vmcnt(14)
; #define GAS __attribute__((address_space(1)))
; __device__ __forceinline__ void unpack8(const v4u v, float (&f)[8]) { f[0] = bflo(v.x); f[1] = bfhi(v.x); f[2] = bflo(v.y); f[3] = bfhi(v.y); f[4] = bflo(v.z); f[5] = bfhi(v.z); f[6] = bflo(v.w); f[7] = bfhi(v.w); }
; __device__ __forceinline__ v4u pack8(const float (&f)[8]) { v4u o; o.x = cvt_pk_bf16(f[0], f[1]); o.y = cvt_pk_bf16(f[2], f[3]); o.z = cvt_pk_bf16(f[4], f[5]); o.w = cvt_pk_bf16(f[6], f[7]); return o; }
; __device__ __forceinline__ float sigmoidf_(float x) { return __builtin_amdgcn_rcpf(1.f + __expf(-x)); }
;     __device__ __forceinline__ void operator()(const f32x4 (&acc)[2][2][4][2], const pg8::Unit& u, int wr, int wc, int fr, int fq) const {
;     ...
;         for (int bj = 0; bj < 2; ++bj) { const int col = col0 + bj * 128;
;             const f32x4 b0 = *(const GAS f32x4*)(bgate + WHICH * DM + col), b1 = *(const GAS f32x4*)(bgate + WHICH * DM + col + 4);
; #pragma unroll
;             for (int aim = 0; aim < 4; ++aim) { const int ai = aim >> 1, mb = (aim & 1) * 2;
;                 v4u gv[4], tv[4];
; #pragma unroll
;                 for (int m = mb; m < mb + 2; ++m) { const int row = row0 + ai * 128 + m * 16;
;                     gv[m] = __builtin_nontemporal_load((const GAS v4u*)(proj + (size_t)row * NPROJ + OFF_GATE + WHICH * DM + col));
;                     if (WHICH == 1) tv[m] = *(const GAS v4u*)(ta + (size_t)row * DM + col); }
; #pragma unroll
;                 for (int m = mb; m < mb + 2; ++m) { const int row = row0 + ai * 128 + m * 16; float g[8]; unpack8(gv[m], g);
;                     const f32x4 a0 = acc[ai][bj][m][0], a1 = acc[ai][bj][m][1]; float r[8];
; #pragma unroll
;                     for (int e = 0; e < 4; ++e) { r[e] = sigmoidf_(g[e] + b0[e]) * a0[e]; r[4 + e] = sigmoidf_(g[4 + e] + b1[e]) * a1[e]; }
;                     if (WHICH == 0) *(GAS v4u*)(ta + (size_t)row * DM + col) = pack8(r);
;                     else { float tf[8]; unpack8(tv[m], tf);
; #pragma unroll
;                         for (int e = 0; e < 8; ++e) r[e] += tf[e];
;                         *(GAS v4u*)(mix + (size_t)row * DM + col) = pack8(r); } }
	v_lshlrev_b32_e32 v144, 16, v202
	v_and_b32_e32 v108, 0xffff0000, v202
	v_lshlrev_b32_e32 v145, 16, v203
	v_and_b32_e32 v109, 0xffff0000, v203
	v_lshlrev_b32_e32 v146, 16, v204
	v_add_f32_e32 v144, v104, v144
	v_add_f32_e32 v108, v105, v108
	v_and_b32_e32 v110, 0xffff0000, v204
	v_lshlrev_b32_e32 v147, 16, v205
	v_and_b32_e32 v111, 0xffff0000, v205
	v_mul_f32_e32 v144, 0xbfb8aa3b, v144
	v_add_f32_e32 v146, v100, v146
	v_mul_f32_e32 v108, 0xbfb8aa3b, v108
	v_add_f32_e32 v145, v106, v145
	v_add_f32_e32 v109, v107, v109
	v_exp_f32_e32 v144, v144
	v_mul_f32_e32 v146, 0xbfb8aa3b, v146
	v_exp_f32_e32 v108, v108
	v_add_f32_e32 v110, v101, v110
	v_mul_f32_e32 v145, 0xbfb8aa3b, v145
	v_add_f32_e32 v147, v102, v147
	v_mul_f32_e32 v109, 0xbfb8aa3b, v109
	v_add_f32_e32 v111, v103, v111
	v_exp_f32_e32 v146, v146
	v_mul_f32_e32 v110, 0xbfb8aa3b, v110
	v_exp_f32_e32 v145, v145
	v_mul_f32_e32 v147, 0xbfb8aa3b, v147
	v_exp_f32_e32 v109, v109
	v_mul_f32_e32 v111, 0xbfb8aa3b, v111
	v_exp_f32_e32 v110, v110
	v_exp_f32_e32 v147, v147
	v_exp_f32_e32 v111, v111
	v_add_f32_e32 v144, 1.0, v144
	v_add_f32_e32 v108, 1.0, v108
	v_rcp_f32_e32 v144, v144
	v_add_f32_e32 v146, 1.0, v146
	v_rcp_f32_e32 v108, v108
	v_add_f32_e32 v145, 1.0, v145
	v_add_f32_e32 v109, 1.0, v109
	v_rcp_f32_e32 v146, v146
	v_add_f32_e32 v110, 1.0, v110
	v_rcp_f32_e32 v145, v145
	v_add_f32_e32 v147, 1.0, v147
	v_rcp_f32_e32 v109, v109
	v_add_f32_e32 v111, 1.0, v111
	v_rcp_f32_e32 v110, v110
	v_rcp_f32_e32 v147, v147
	v_rcp_f32_e32 v111, v111
	s_waitcnt vmcnt(11)
	v_lshlrev_b32_e32 v159, 16, v234
	v_and_b32_e32 v124, 0xffff0000, v234
	v_lshlrev_b32_e32 v170, 16, v235
	v_and_b32_e32 v125, 0xffff0000, v235
	v_lshlrev_b32_e32 v171, 16, v236
	v_fmac_f32_e32 v159, v80, v144
	v_fmac_f32_e32 v124, v81, v108
	v_lshl_add_u64 v[80:81], s[46:47], 0, v[94:95]
	v_and_b32_e32 v126, 0xffff0000, v236
	v_lshlrev_b32_e32 v184, 16, v237
	v_and_b32_e32 v127, 0xffff0000, v237
	v_fmac_f32_e32 v170, v82, v145
	v_fmac_f32_e32 v125, v83, v109
	v_fmac_f32_e32 v171, v76, v146
	v_cvt_pk_bf16_f32 v76, v159, v124
	v_lshl_add_u64 v[82:83], v[80:81], 0, v[168:169]
	v_fmac_f32_e32 v126, v77, v110
	v_fmac_f32_e32 v184, v78, v147
	v_fmac_f32_e32 v127, v79, v111
	v_cvt_pk_bf16_f32 v77, v170, v125
	v_cvt_pk_bf16_f32 v78, v171, v126
	v_cvt_pk_bf16_f32 v79, v184, v127
	global_store_dwordx4 v[82:83], v[76:79], off
	v_or_b32_e32 v251, 0x80, v158
	v_ashrrev_i32_e32 v250, 31, v251
	v_mov_b32_e32 v246, v251
	v_mov_b32_e32 v247, v250
	v_lshlrev_b64 v[248:249], 1, v[246:247]
	v_lshl_add_u64 v[244:245], v[130:131], 0, v[248:249]
	global_load_dwordx4 v[234:237], v[244:245], off nt
	v_lshl_add_u64 v[250:251], s[44:45], 0, v[132:133]
	v_or_b32_e32 v249, 0x80, v158
	v_ashrrev_i32_e32 v248, 31, v249
	v_mov_b32_e32 v244, v249
	v_mov_b32_e32 v245, v248
	v_lshlrev_b64 v[246:247], 1, v[244:245]
	v_lshl_add_u64 v[212:213], v[250:251], 0, v[246:247]
	global_load_dwordx4 v[204:207], v[212:213], off
	v_or_b32_e32 v251, 0x80, v158
	v_ashrrev_i32_e32 v250, 31, v251
	v_mov_b32_e32 v246, v251
	v_mov_b32_e32 v247, v250
	v_lshlrev_b64 v[248:249], 1, v[246:247]
	v_lshl_add_u64 v[244:245], v[134:135], 0, v[248:249]
	global_load_dwordx4 v[184:187], v[244:245], off nt
	v_lshl_add_u64 v[250:251], s[44:45], 0, v[138:139]
	v_or_b32_e32 v249, 0x80, v158
	v_ashrrev_i32_e32 v248, 31, v249
	v_mov_b32_e32 v244, v249
	v_mov_b32_e32 v245, v248
	v_lshlrev_b64 v[246:247], 1, v[244:245]
	v_lshl_add_u64 v[212:213], v[250:251], 0, v[246:247]
	global_load_dwordx4 v[144:147], v[212:213], off
	s_waitcnt vmcnt(15)
	v_lshlrev_b32_e32 v80, 16, v232
	v_and_b32_e32 v81, 0xffff0000, v232
	v_lshlrev_b32_e32 v76, 16, v230
	v_and_b32_e32 v77, 0xffff0000, v230
	v_and_b32_e32 v79, 0xffff0000, v231
	v_add_f32_e32 v76, v104, v76
	v_lshlrev_b32_e32 v78, 16, v231
	v_mul_f32_e32 v76, 0xbfb8aa3b, v76
	v_add_f32_e32 v77, v105, v77
	v_add_f32_e32 v79, v107, v79
	v_lshlrev_b32_e32 v108, 16, v233
	v_and_b32_e32 v109, 0xffff0000, v233
	v_exp_f32_e32 v76, v76
	v_add_f32_e32 v80, v100, v80
	v_mul_f32_e32 v77, 0xbfb8aa3b, v77
	v_add_f32_e32 v81, v101, v81
	v_add_f32_e32 v78, v106, v78
	v_mul_f32_e32 v79, 0xbfb8aa3b, v79
	v_mul_f32_e32 v80, 0xbfb8aa3b, v80
	v_exp_f32_e32 v77, v77
	v_mul_f32_e32 v81, 0xbfb8aa3b, v81
	v_mul_f32_e32 v78, 0xbfb8aa3b, v78
	v_add_f32_e32 v100, v102, v108
	v_exp_f32_e32 v79, v79
	v_add_f32_e32 v101, v103, v109
	v_exp_f32_e32 v80, v80
	v_exp_f32_e32 v81, v81
	v_exp_f32_e32 v78, v78
	v_mul_f32_e32 v100, 0xbfb8aa3b, v100
	v_mul_f32_e32 v101, 0xbfb8aa3b, v101
	v_exp_f32_e32 v100, v100
	v_exp_f32_e32 v101, v101
	v_add_f32_e32 v76, 1.0, v76
	v_rcp_f32_e32 v76, v76
	v_add_f32_e32 v77, 1.0, v77
	v_add_f32_e32 v79, 1.0, v79
	v_add_f32_e32 v80, 1.0, v80
	v_rcp_f32_e32 v77, v77
	v_add_f32_e32 v81, 1.0, v81
	v_add_f32_e32 v78, 1.0, v78
	v_rcp_f32_e32 v79, v79
	v_rcp_f32_e32 v80, v80
	v_rcp_f32_e32 v81, v81
	v_rcp_f32_e32 v78, v78
	v_add_f32_e32 v100, 1.0, v100
	v_add_f32_e32 v101, 1.0, v101
	v_rcp_f32_e32 v100, v100
	v_rcp_f32_e32 v101, v101
	s_waitcnt vmcnt(14)
; #define GAS __attribute__((address_space(1)))
; __device__ __forceinline__ void unpack8(const v4u v, float (&f)[8]) { f[0] = bflo(v.x); f[1] = bfhi(v.x); f[2] = bflo(v.y); f[3] = bfhi(v.y); f[4] = bflo(v.z); f[5] = bfhi(v.z); f[6] = bflo(v.w); f[7] = bfhi(v.w); }
; __device__ __forceinline__ v4u pack8(const float (&f)[8]) { v4u o; o.x = cvt_pk_bf16(f[0], f[1]); o.y = cvt_pk_bf16(f[2], f[3]); o.z = cvt_pk_bf16(f[4], f[5]); o.w = cvt_pk_bf16(f[6], f[7]); return o; }
; __device__ __forceinline__ float sigmoidf_(float x) { return __builtin_amdgcn_rcpf(1.f + __expf(-x)); }
;     __device__ __forceinline__ void operator()(const f32x4 (&acc)[2][2][4][2], const pg8::Unit& u, int wr, int wc, int fr, int fq) const {
;     ...
;         for (int bj = 0; bj < 2; ++bj) { const int col = col0 + bj * 128;
;             const f32x4 b0 = *(const GAS f32x4*)(bgate + WHICH * DM + col), b1 = *(const GAS f32x4*)(bgate + WHICH * DM + col + 4);
; #pragma unroll
;             for (int aim = 0; aim < 4; ++aim) { const int ai = aim >> 1, mb = (aim & 1) * 2;
;                 v4u gv[4], tv[4];
; #pragma unroll
;                 for (int m = mb; m < mb + 2; ++m) { const int row = row0 + ai * 128 + m * 16;
;                     gv[m] = __builtin_nontemporal_load((const GAS v4u*)(proj + (size_t)row * NPROJ + OFF_GATE + WHICH * DM + col));
;                     if (WHICH == 1) tv[m] = *(const GAS v4u*)(ta + (size_t)row * DM + col); }
; #pragma unroll
;                 for (int m = mb; m < mb + 2; ++m) { const int row = row0 + ai * 128 + m * 16; float g[8]; unpack8(gv[m], g);
;                     const f32x4 a0 = acc[ai][bj][m][0], a1 = acc[ai][bj][m][1]; float r[8];
; #pragma unroll
;                     for (int e = 0; e < 4; ++e) { r[e] = sigmoidf_(g[e] + b0[e]) * a0[e]; r[4 + e] = sigmoidf_(g[4 + e] + b1[e]) * a1[e]; }
;                     if (WHICH == 0) *(GAS v4u*)(ta + (size_t)row * DM + col) = pack8(r);
;                     else { float tf[8]; unpack8(tv[m], tf);
; #pragma unroll
;                         for (int e = 0; e < 8; ++e) r[e] += tf[e];
;                         *(GAS v4u*)(mix + (size_t)row * DM + col) = pack8(r); } }
	v_lshlrev_b32_e32 v102, 16, v198
	v_and_b32_e32 v84, 0xffff0000, v198
	v_lshlrev_b32_e32 v103, 16, v199
	v_and_b32_e32 v85, 0xffff0000, v199
	v_fmac_f32_e32 v102, v72, v76
	v_or_b32_e32 v76, 0x80, v158
	v_lshlrev_b32_e32 v104, 16, v200
	v_and_b32_e32 v86, 0xffff0000, v200
	v_fmac_f32_e32 v84, v73, v77
	v_fmac_f32_e32 v85, v75, v79
	v_lshl_add_u64 v[72:73], s[46:47], 0, v[98:99]
	v_ashrrev_i32_e32 v77, 31, v76
	v_lshlrev_b32_e32 v105, 16, v201
	v_and_b32_e32 v87, 0xffff0000, v201
	v_fmac_f32_e32 v103, v74, v78
	v_fmac_f32_e32 v104, v68, v80
	v_fmac_f32_e32 v86, v69, v81
	v_cvt_pk_bf16_f32 v68, v102, v84
	v_cvt_pk_bf16_f32 v69, v103, v85
	v_lshl_add_u64 v[80:81], v[72:73], 0, v[168:169]
	v_lshlrev_b64 v[84:85], 1, v[76:77]
	v_fmac_f32_e32 v105, v70, v100
	v_fmac_f32_e32 v87, v71, v101
	v_cvt_pk_bf16_f32 v70, v104, v86
	v_cvt_pk_bf16_f32 v71, v105, v87
	global_store_dwordx4 v[80:81], v[68:71], off
	v_lshl_add_u64 v[250:251], v[114:115], 0, v[84:85]
	global_load_dwordx4 v[246:249], v[250:251], off nt
	v_lshl_add_u64 v[250:251], s[44:45], 0, v[118:119]
	v_lshl_add_u64 v[244:245], v[250:251], 0, v[84:85]
	global_load_dwordx4 v[230:233], v[244:245], off
	v_lshl_add_u64 v[250:251], v[120:121], 0, v[84:85]
	global_load_dwordx4 v[200:203], v[250:251], off nt
	v_lshl_add_u64 v[250:251], s[44:45], 0, v[122:123]
	v_lshl_add_u64 v[244:245], v[250:251], 0, v[84:85]
	global_load_dwordx4 v[168:171], v[244:245], off
	v_lshl_add_u64 v[250:251], v[90:91], 0, v[84:85]
	global_load_dwordx4 v[108:111], v[250:251], off nt
	v_lshl_add_u64 v[250:251], s[44:45], 0, v[94:95]
	v_lshl_add_u64 v[244:245], v[250:251], 0, v[84:85]
	global_load_dwordx4 v[68:71], v[244:245], off
	v_lshl_add_u64 v[72:73], v[76:77], 2, s[14:15]
	v_lshl_add_u64 v[76:77], v[162:163], 0, v[84:85]
	s_nop 0
	s_nop 0
	s_nop 0
	s_nop 0
	s_nop 0
	v_lshl_add_u64 v[76:77], s[44:45], 0, v[160:161]
	v_lshl_add_u64 v[76:77], v[76:77], 0, v[84:85]
	s_nop 0
	v_lshl_add_u64 v[76:77], v[164:165], 0, v[84:85]
	s_nop 0
	v_lshl_add_u64 v[76:77], s[44:45], 0, v[166:167]
	v_lshl_add_u64 v[76:77], v[76:77], 0, v[84:85]
	s_nop 0
	s_waitcnt vmcnt(16)
	v_lshlrev_b32_e32 v86, 16, v218
	v_and_b32_e32 v87, 0xffff0000, v218
	v_lshlrev_b32_e32 v100, 16, v219
	v_and_b32_e32 v101, 0xffff0000, v219
	v_lshlrev_b32_e32 v124, 16, v220
	v_and_b32_e32 v102, 0xffff0000, v220
	v_lshlrev_b32_e32 v125, 16, v221
	v_and_b32_e32 v103, 0xffff0000, v221
	v_add_f32_e32 v86, v222, v86
	v_add_f32_e32 v124, v226, v124
	v_add_f32_e32 v87, v223, v87
	v_add_f32_e32 v102, v227, v102
	v_add_f32_e32 v100, v224, v100
	v_add_f32_e32 v125, v228, v125
	v_add_f32_e32 v101, v225, v101
	v_add_f32_e32 v103, v229, v103
	v_mul_f32_e32 v86, 0xbfb8aa3b, v86
	v_mul_f32_e32 v124, 0xbfb8aa3b, v124
	v_mul_f32_e32 v87, 0xbfb8aa3b, v87
	v_mul_f32_e32 v102, 0xbfb8aa3b, v102
	v_mul_f32_e32 v100, 0xbfb8aa3b, v100
	v_mul_f32_e32 v125, 0xbfb8aa3b, v125
	v_mul_f32_e32 v101, 0xbfb8aa3b, v101
	v_mul_f32_e32 v103, 0xbfb8aa3b, v103
	v_exp_f32_e32 v86, v86
	v_exp_f32_e32 v124, v124
	v_exp_f32_e32 v87, v87
	v_exp_f32_e32 v102, v102
	v_exp_f32_e32 v100, v100
	v_exp_f32_e32 v125, v125
	v_exp_f32_e32 v101, v101
	v_exp_f32_e32 v103, v103
	v_add_f32_e32 v86, 1.0, v86
	v_add_f32_e32 v124, 1.0, v124
	v_add_f32_e32 v87, 1.0, v87
	v_add_f32_e32 v102, 1.0, v102
	v_add_f32_e32 v100, 1.0, v100
	v_add_f32_e32 v125, 1.0, v125
	v_add_f32_e32 v101, 1.0, v101
	v_add_f32_e32 v103, 1.0, v103
	v_rcp_f32_e32 v86, v86
	v_rcp_f32_e32 v124, v124
	v_rcp_f32_e32 v87, v87
	v_rcp_f32_e32 v102, v102
	v_rcp_f32_e32 v100, v100
	v_rcp_f32_e32 v125, v125
	v_rcp_f32_e32 v101, v101
	v_rcp_f32_e32 v103, v103
	s_waitcnt vmcnt(15)
	v_lshlrev_b32_e32 v126, 16, v194
	v_and_b32_e32 v104, 0xffff0000, v194
	v_lshlrev_b32_e32 v127, 16, v195
	v_and_b32_e32 v105, 0xffff0000, v195
	v_lshlrev_b32_e32 v140, 16, v196
	v_and_b32_e32 v106, 0xffff0000, v196
	v_lshlrev_b32_e32 v141, 16, v197
	v_and_b32_e32 v107, 0xffff0000, v197
	v_fmac_f32_e32 v126, v64, v86
	v_fmac_f32_e32 v104, v65, v87
	v_fmac_f32_e32 v127, v66, v100
	v_fmac_f32_e32 v105, v67, v101
	v_fmac_f32_e32 v140, v60, v124
	v_fmac_f32_e32 v106, v61, v102
	v_fmac_f32_e32 v141, v62, v125
	v_fmac_f32_e32 v107, v63, v103
	v_cvt_pk_bf16_f32 v60, v126, v104
	v_cvt_pk_bf16_f32 v61, v127, v105
	v_cvt_pk_bf16_f32 v62, v140, v106
	v_cvt_pk_bf16_f32 v63, v141, v107
	global_store_dwordx4 v[136:137], v[60:63], off offset:256
	v_lshl_add_u64 v[250:251], v[96:97], 0, v[84:85]
	global_load_dwordx4 v[218:221], v[250:251], off nt
	v_lshl_add_u64 v[250:251], s[44:45], 0, v[98:99]
	v_lshl_add_u64 v[244:245], v[250:251], 0, v[84:85]
	global_load_dwordx4 v[196:199], v[244:245], off
	s_waitcnt vmcnt(17)
	v_lshlrev_b32_e32 v64, 16, v216
	v_and_b32_e32 v65, 0xffff0000, v216
	v_lshlrev_b32_e32 v60, 16, v214
	v_and_b32_e32 v61, 0xffff0000, v214
	v_lshlrev_b32_e32 v62, 16, v215
	v_and_b32_e32 v63, 0xffff0000, v215
	v_lshlrev_b32_e32 v66, 16, v217
	v_and_b32_e32 v67, 0xffff0000, v217
	v_add_f32_e32 v60, v222, v60
	v_add_f32_e32 v64, v226, v64
	v_add_f32_e32 v61, v223, v61
	v_add_f32_e32 v65, v227, v65
	v_add_f32_e32 v62, v224, v62
	v_add_f32_e32 v63, v225, v63
	v_mul_f32_e32 v60, 0xbfb8aa3b, v60
	v_mul_f32_e32 v64, 0xbfb8aa3b, v64
	v_mul_f32_e32 v61, 0xbfb8aa3b, v61
	v_mul_f32_e32 v65, 0xbfb8aa3b, v65
	v_mul_f32_e32 v62, 0xbfb8aa3b, v62
	v_add_f32_e32 v66, v228, v66
	v_mul_f32_e32 v63, 0xbfb8aa3b, v63
	v_add_f32_e32 v67, v229, v67
	v_exp_f32_e32 v60, v60
	v_exp_f32_e32 v64, v64
	v_exp_f32_e32 v61, v61
	v_exp_f32_e32 v65, v65
	v_exp_f32_e32 v62, v62
	v_mul_f32_e32 v66, 0xbfb8aa3b, v66
	v_exp_f32_e32 v63, v63
	v_mul_f32_e32 v67, 0xbfb8aa3b, v67
	v_exp_f32_e32 v66, v66
	v_exp_f32_e32 v67, v67
	v_add_f32_e32 v60, 1.0, v60
	v_add_f32_e32 v64, 1.0, v64
	v_add_f32_e32 v61, 1.0, v61
	v_add_f32_e32 v65, 1.0, v65
	v_add_f32_e32 v62, 1.0, v62
	v_add_f32_e32 v63, 1.0, v63
	v_rcp_f32_e32 v60, v60
	v_rcp_f32_e32 v64, v64
	v_rcp_f32_e32 v61, v61
	v_rcp_f32_e32 v65, v65
	v_rcp_f32_e32 v62, v62
	v_add_f32_e32 v66, 1.0, v66
	v_rcp_f32_e32 v63, v63
	v_add_f32_e32 v67, 1.0, v67
	v_rcp_f32_e32 v66, v66
	v_rcp_f32_e32 v67, v67
	s_waitcnt vmcnt(15)
; #define GAS __attribute__((address_space(1)))
; __device__ __forceinline__ void unpack8(const v4u v, float (&f)[8]) { f[0] = bflo(v.x); f[1] = bfhi(v.x); f[2] = bflo(v.y); f[3] = bfhi(v.y); f[4] = bflo(v.z); f[5] = bfhi(v.z); f[6] = bflo(v.w); f[7] = bfhi(v.w); }
; __device__ __forceinline__ v4u pack8(const float (&f)[8]) { v4u o; o.x = cvt_pk_bf16(f[0], f[1]); o.y = cvt_pk_bf16(f[2], f[3]); o.z = cvt_pk_bf16(f[4], f[5]); o.w = cvt_pk_bf16(f[6], f[7]); return o; }
; __device__ __forceinline__ float sigmoidf_(float x) { return __builtin_amdgcn_rcpf(1.f + __expf(-x)); }
;     __device__ __forceinline__ void operator()(const f32x4 (&acc)[2][2][4][2], const pg8::Unit& u, int wr, int wc, int fr, int fq) const {
;     ...
;             for (int aim = 0; aim < 4; ++aim) { const int ai = aim >> 1, mb = (aim & 1) * 2;
;                 v4u gv[4], tv[4];
; #pragma unroll
;                 for (int m = mb; m < mb + 2; ++m) { const int row = row0 + ai * 128 + m * 16;
;                     gv[m] = __builtin_nontemporal_load((const GAS v4u*)(proj + (size_t)row * NPROJ + OFF_GATE + WHICH * DM + col));
;                     if (WHICH == 1) tv[m] = *(const GAS v4u*)(ta + (size_t)row * DM + col); }
; #pragma unroll
;                 for (int m = mb; m < mb + 2; ++m) { const int row = row0 + ai * 128 + m * 16; float g[8]; unpack8(gv[m], g);
;                     const f32x4 a0 = acc[ai][bj][m][0], a1 = acc[ai][bj][m][1]; float r[8];
; #pragma unroll
;                     for (int e = 0; e < 4; ++e) { r[e] = sigmoidf_(g[e] + b0[e]) * a0[e]; r[4 + e] = sigmoidf_(g[4 + e] + b1[e]) * a1[e]; }
;                     if (WHICH == 0) *(GAS v4u*)(ta + (size_t)row * DM + col) = pack8(r);
;                     else { float tf[8]; unpack8(tv[m], tf);
; #pragma unroll
;                         for (int e = 0; e < 8; ++e) r[e] += tf[e];
;                         *(GAS v4u*)(mix + (size_t)row * DM + col) = pack8(r); } }
	v_lshlrev_b32_e32 v86, 16, v208
	v_and_b32_e32 v76, 0xffff0000, v208
	v_lshlrev_b32_e32 v87, 16, v209
	v_and_b32_e32 v77, 0xffff0000, v209
	v_lshlrev_b32_e32 v100, 16, v210
	v_and_b32_e32 v78, 0xffff0000, v210
	v_lshlrev_b32_e32 v101, 16, v211
	v_and_b32_e32 v79, 0xffff0000, v211
	v_fmac_f32_e32 v86, v56, v60
	v_fmac_f32_e32 v76, v57, v61
	v_fmac_f32_e32 v87, v58, v62
	v_fmac_f32_e32 v77, v59, v63
	v_fmac_f32_e32 v100, v52, v64
	v_fmac_f32_e32 v78, v53, v65
	v_cvt_pk_bf16_f32 v52, v86, v76
	v_cvt_pk_bf16_f32 v53, v87, v77
	v_fmac_f32_e32 v101, v54, v66
	v_fmac_f32_e32 v79, v55, v67
	v_cvt_pk_bf16_f32 v54, v100, v78
	v_cvt_pk_bf16_f32 v55, v101, v79
	global_store_dwordx4 v[128:129], v[52:55], off offset:256
	s_nop 1
	v_lshl_add_u64 v[52:53], v[130:131], 0, v[84:85]
	s_nop 0
	v_lshl_add_u64 v[52:53], s[44:45], 0, v[132:133]
	v_lshl_add_u64 v[52:53], v[52:53], 0, v[84:85]
	s_nop 0
	v_lshl_add_u64 v[52:53], v[134:135], 0, v[84:85]
	s_nop 0
	v_lshl_add_u64 v[52:53], s[44:45], 0, v[138:139]
	v_lshl_add_u64 v[52:53], v[52:53], 0, v[84:85]
	s_nop 0
	s_waitcnt vmcnt(14)
	v_lshlrev_b32_e32 v76, 16, v234
	v_and_b32_e32 v56, 0xffff0000, v234
	v_lshlrev_b32_e32 v77, 16, v235
	v_and_b32_e32 v57, 0xffff0000, v235
	v_lshlrev_b32_e32 v78, 16, v236
	v_and_b32_e32 v58, 0xffff0000, v236
	v_lshlrev_b32_e32 v79, 16, v237
	v_and_b32_e32 v59, 0xffff0000, v237
	v_add_f32_e32 v76, v222, v76
	v_add_f32_e32 v78, v226, v78
	v_add_f32_e32 v56, v223, v56
	v_add_f32_e32 v58, v227, v58
	v_add_f32_e32 v77, v224, v77
	v_add_f32_e32 v79, v228, v79
	v_add_f32_e32 v57, v225, v57
	v_add_f32_e32 v59, v229, v59
	v_mul_f32_e32 v76, 0xbfb8aa3b, v76
	v_mul_f32_e32 v78, 0xbfb8aa3b, v78
	v_mul_f32_e32 v56, 0xbfb8aa3b, v56
	v_mul_f32_e32 v58, 0xbfb8aa3b, v58
	v_mul_f32_e32 v77, 0xbfb8aa3b, v77
	v_mul_f32_e32 v79, 0xbfb8aa3b, v79
	v_mul_f32_e32 v57, 0xbfb8aa3b, v57
	v_mul_f32_e32 v59, 0xbfb8aa3b, v59
	v_exp_f32_e32 v76, v76
	v_exp_f32_e32 v78, v78
	v_exp_f32_e32 v56, v56
	v_exp_f32_e32 v58, v58
	v_exp_f32_e32 v77, v77
	v_exp_f32_e32 v79, v79
	v_exp_f32_e32 v57, v57
	v_exp_f32_e32 v59, v59
	v_add_f32_e32 v76, 1.0, v76
	v_add_f32_e32 v78, 1.0, v78
	v_add_f32_e32 v56, 1.0, v56
	v_add_f32_e32 v58, 1.0, v58
	v_add_f32_e32 v77, 1.0, v77
	v_add_f32_e32 v79, 1.0, v79
	v_add_f32_e32 v57, 1.0, v57
	v_add_f32_e32 v59, 1.0, v59
	v_rcp_f32_e32 v76, v76
	v_rcp_f32_e32 v78, v78
	v_rcp_f32_e32 v56, v56
	v_rcp_f32_e32 v58, v58
	v_rcp_f32_e32 v77, v77
	v_rcp_f32_e32 v79, v79
	v_rcp_f32_e32 v57, v57
	v_rcp_f32_e32 v59, v59
	s_waitcnt vmcnt(13)
	v_lshlrev_b32_e32 v86, 16, v204
	v_and_b32_e32 v60, 0xffff0000, v204
	v_lshlrev_b32_e32 v87, 16, v205
	v_and_b32_e32 v61, 0xffff0000, v205
	v_lshlrev_b32_e32 v100, 16, v206
	v_and_b32_e32 v62, 0xffff0000, v206
	v_lshlrev_b32_e32 v101, 16, v207
	v_and_b32_e32 v63, 0xffff0000, v207
	v_fmac_f32_e32 v86, v48, v76
	v_fmac_f32_e32 v60, v49, v56
	v_fmac_f32_e32 v87, v50, v77
	v_fmac_f32_e32 v61, v51, v57
	v_fmac_f32_e32 v100, v44, v78
	v_fmac_f32_e32 v62, v45, v58
	v_fmac_f32_e32 v101, v46, v79
	v_fmac_f32_e32 v63, v47, v59
	v_cvt_pk_bf16_f32 v44, v86, v60
	v_cvt_pk_bf16_f32 v45, v87, v61
	v_cvt_pk_bf16_f32 v46, v100, v62
	v_cvt_pk_bf16_f32 v47, v101, v63
	global_store_dwordx4 v[116:117], v[44:47], off offset:256
	s_waitcnt vmcnt(13)
	v_lshlrev_b32_e32 v48, 16, v186
	v_and_b32_e32 v49, 0xffff0000, v186
	v_lshlrev_b32_e32 v44, 16, v184
	v_and_b32_e32 v45, 0xffff0000, v184
	v_lshlrev_b32_e32 v46, 16, v185
	v_and_b32_e32 v47, 0xffff0000, v185
	v_lshlrev_b32_e32 v50, 16, v187
	v_and_b32_e32 v51, 0xffff0000, v187
	v_add_f32_e32 v44, v222, v44
	v_add_f32_e32 v48, v226, v48
	v_add_f32_e32 v45, v223, v45
	v_add_f32_e32 v49, v227, v49
	v_add_f32_e32 v46, v224, v46
	v_add_f32_e32 v47, v225, v47
	v_mul_f32_e32 v44, 0xbfb8aa3b, v44
	v_mul_f32_e32 v48, 0xbfb8aa3b, v48
	v_mul_f32_e32 v45, 0xbfb8aa3b, v45
	v_mul_f32_e32 v49, 0xbfb8aa3b, v49
	v_mul_f32_e32 v46, 0xbfb8aa3b, v46
	v_add_f32_e32 v50, v228, v50
	v_mul_f32_e32 v47, 0xbfb8aa3b, v47
	v_add_f32_e32 v51, v229, v51
	v_exp_f32_e32 v44, v44
	v_exp_f32_e32 v48, v48
	v_exp_f32_e32 v45, v45
	v_exp_f32_e32 v49, v49
	v_exp_f32_e32 v46, v46
	v_mul_f32_e32 v50, 0xbfb8aa3b, v50
	v_exp_f32_e32 v47, v47
	v_mul_f32_e32 v51, 0xbfb8aa3b, v51
	v_exp_f32_e32 v50, v50
	v_exp_f32_e32 v51, v51
	v_add_f32_e32 v44, 1.0, v44
	v_add_f32_e32 v48, 1.0, v48
	v_add_f32_e32 v45, 1.0, v45
	v_add_f32_e32 v49, 1.0, v49
	v_add_f32_e32 v46, 1.0, v46
	v_add_f32_e32 v47, 1.0, v47
	v_rcp_f32_e32 v44, v44
	v_rcp_f32_e32 v48, v48
	v_rcp_f32_e32 v45, v45
	v_rcp_f32_e32 v49, v49
	v_rcp_f32_e32 v46, v46
	v_add_f32_e32 v50, 1.0, v50
	v_rcp_f32_e32 v47, v47
	v_add_f32_e32 v51, 1.0, v51
	v_rcp_f32_e32 v50, v50
	v_rcp_f32_e32 v51, v51
	s_waitcnt vmcnt(12)
	v_lshlrev_b32_e32 v56, 16, v144
	v_and_b32_e32 v52, 0xffff0000, v144
	v_lshlrev_b32_e32 v57, 16, v145
	v_and_b32_e32 v53, 0xffff0000, v145
	v_lshlrev_b32_e32 v58, 16, v146
	v_and_b32_e32 v54, 0xffff0000, v146
	v_lshlrev_b32_e32 v59, 16, v147
	v_and_b32_e32 v55, 0xffff0000, v147
	v_fmac_f32_e32 v56, v40, v44
	v_fmac_f32_e32 v52, v41, v45
	v_fmac_f32_e32 v57, v42, v46
	v_fmac_f32_e32 v53, v43, v47
	v_fmac_f32_e32 v58, v36, v48
	v_fmac_f32_e32 v54, v37, v49
	v_cvt_pk_bf16_f32 v36, v56, v52
	v_cvt_pk_bf16_f32 v37, v57, v53
	v_fmac_f32_e32 v59, v38, v50
	v_fmac_f32_e32 v55, v39, v51
	v_cvt_pk_bf16_f32 v38, v58, v54
	v_cvt_pk_bf16_f32 v39, v59, v55
	global_store_dwordx4 v[112:113], v[36:39], off offset:256
	s_nop 1
	v_lshl_add_u64 v[36:37], v[114:115], 0, v[84:85]
	s_nop 0
	v_lshl_add_u64 v[36:37], s[44:45], 0, v[118:119]
	v_lshl_add_u64 v[36:37], v[36:37], 0, v[84:85]
	s_nop 0
	v_lshl_add_u64 v[36:37], v[120:121], 0, v[84:85]
	s_nop 0
	v_lshl_add_u64 v[36:37], s[44:45], 0, v[122:123]
	v_lshl_add_u64 v[36:37], v[36:37], 0, v[84:85]
	s_nop 0
	s_waitcnt vmcnt(11)
; #define GAS __attribute__((address_space(1)))
; __device__ __forceinline__ void unpack8(const v4u v, float (&f)[8]) { f[0] = bflo(v.x); f[1] = bfhi(v.x); f[2] = bflo(v.y); f[3] = bfhi(v.y); f[4] = bflo(v.z); f[5] = bfhi(v.z); f[6] = bflo(v.w); f[7] = bfhi(v.w); }
; __device__ __forceinline__ v4u pack8(const float (&f)[8]) { v4u o; o.x = cvt_pk_bf16(f[0], f[1]); o.y = cvt_pk_bf16(f[2], f[3]); o.z = cvt_pk_bf16(f[4], f[5]); o.w = cvt_pk_bf16(f[6], f[7]); return o; }
; __device__ __forceinline__ float sigmoidf_(float x) { return __builtin_amdgcn_rcpf(1.f + __expf(-x)); }
;     __device__ __forceinline__ void operator()(const f32x4 (&acc)[2][2][4][2], const pg8::Unit& u, int wr, int wc, int fr, int fq) const {
;     ...
;             for (int aim = 0; aim < 4; ++aim) { const int ai = aim >> 1, mb = (aim & 1) * 2;
;                 v4u gv[4], tv[4];
; #pragma unroll
;                 for (int m = mb; m < mb + 2; ++m) { const int row = row0 + ai * 128 + m * 16;
;                     gv[m] = __builtin_nontemporal_load((const GAS v4u*)(proj + (size_t)row * NPROJ + OFF_GATE + WHICH * DM + col));
;                     if (WHICH == 1) tv[m] = *(const GAS v4u*)(ta + (size_t)row * DM + col); }
; #pragma unroll
;                 for (int m = mb; m < mb + 2; ++m) { const int row = row0 + ai * 128 + m * 16; float g[8]; unpack8(gv[m], g);
;                     const f32x4 a0 = acc[ai][bj][m][0], a1 = acc[ai][bj][m][1]; float r[8];
; #pragma unroll
;                     for (int e = 0; e < 4; ++e) { r[e] = sigmoidf_(g[e] + b0[e]) * a0[e]; r[4 + e] = sigmoidf_(g[4 + e] + b1[e]) * a1[e]; }
;                     if (WHICH == 0) *(GAS v4u*)(ta + (size_t)row * DM + col) = pack8(r);
;                     else { float tf[8]; unpack8(tv[m], tf);
; #pragma unroll
;                         for (int e = 0; e < 8; ++e) r[e] += tf[e];
;                         *(GAS v4u*)(mix + (size_t)row * DM + col) = pack8(r); } }
	v_lshlrev_b32_e32 v52, 16, v246
	v_and_b32_e32 v40, 0xffff0000, v246
	v_lshlrev_b32_e32 v53, 16, v247
	v_and_b32_e32 v41, 0xffff0000, v247
	v_lshlrev_b32_e32 v54, 16, v248
	v_and_b32_e32 v42, 0xffff0000, v248
	v_lshlrev_b32_e32 v55, 16, v249
	v_and_b32_e32 v43, 0xffff0000, v249
	v_add_f32_e32 v52, v222, v52
	v_add_f32_e32 v54, v226, v54
	v_add_f32_e32 v40, v223, v40
	v_add_f32_e32 v42, v227, v42
	v_add_f32_e32 v53, v224, v53
	v_add_f32_e32 v55, v228, v55
	v_add_f32_e32 v41, v225, v41
	v_add_f32_e32 v43, v229, v43
	v_mul_f32_e32 v52, 0xbfb8aa3b, v52
	v_mul_f32_e32 v54, 0xbfb8aa3b, v54
	v_mul_f32_e32 v40, 0xbfb8aa3b, v40
	v_mul_f32_e32 v42, 0xbfb8aa3b, v42
	v_mul_f32_e32 v53, 0xbfb8aa3b, v53
	v_mul_f32_e32 v55, 0xbfb8aa3b, v55
	v_mul_f32_e32 v41, 0xbfb8aa3b, v41
	v_mul_f32_e32 v43, 0xbfb8aa3b, v43
	v_exp_f32_e32 v52, v52
	v_exp_f32_e32 v54, v54
	v_exp_f32_e32 v40, v40
	v_exp_f32_e32 v42, v42
	v_exp_f32_e32 v53, v53
	v_exp_f32_e32 v55, v55
	v_exp_f32_e32 v41, v41
	v_exp_f32_e32 v43, v43
	v_add_f32_e32 v52, 1.0, v52
	v_add_f32_e32 v54, 1.0, v54
	v_add_f32_e32 v40, 1.0, v40
	v_add_f32_e32 v42, 1.0, v42
	v_add_f32_e32 v53, 1.0, v53
	v_add_f32_e32 v55, 1.0, v55
	v_add_f32_e32 v41, 1.0, v41
	v_add_f32_e32 v43, 1.0, v43
	v_rcp_f32_e32 v52, v52
	v_rcp_f32_e32 v54, v54
	v_rcp_f32_e32 v40, v40
	v_rcp_f32_e32 v42, v42
	v_rcp_f32_e32 v53, v53
	v_rcp_f32_e32 v55, v55
	v_rcp_f32_e32 v41, v41
	v_rcp_f32_e32 v43, v43
	s_waitcnt vmcnt(10)
	v_lshlrev_b32_e32 v56, 16, v230
	v_and_b32_e32 v44, 0xffff0000, v230
	v_lshlrev_b32_e32 v57, 16, v231
	v_and_b32_e32 v45, 0xffff0000, v231
	v_lshlrev_b32_e32 v58, 16, v232
	v_and_b32_e32 v46, 0xffff0000, v232
	v_lshlrev_b32_e32 v59, 16, v233
	v_and_b32_e32 v47, 0xffff0000, v233
	v_fmac_f32_e32 v56, v32, v52
	v_fmac_f32_e32 v44, v33, v40
	v_fmac_f32_e32 v57, v34, v53
	v_fmac_f32_e32 v45, v35, v41
	v_fmac_f32_e32 v58, v28, v54
	v_fmac_f32_e32 v46, v29, v42
	v_fmac_f32_e32 v59, v30, v55
	v_fmac_f32_e32 v47, v31, v43
	v_cvt_pk_bf16_f32 v28, v56, v44
	v_cvt_pk_bf16_f32 v29, v57, v45
	v_cvt_pk_bf16_f32 v30, v58, v46
	v_cvt_pk_bf16_f32 v31, v59, v47
	global_store_dwordx4 v[92:93], v[28:31], off offset:256
	s_waitcnt vmcnt(10)
	v_lshlrev_b32_e32 v32, 16, v202
	v_and_b32_e32 v33, 0xffff0000, v202
	v_lshlrev_b32_e32 v28, 16, v200
	v_and_b32_e32 v29, 0xffff0000, v200
	v_lshlrev_b32_e32 v30, 16, v201
	v_and_b32_e32 v31, 0xffff0000, v201
	v_lshlrev_b32_e32 v34, 16, v203
	v_and_b32_e32 v35, 0xffff0000, v203
	v_add_f32_e32 v28, v222, v28
	v_add_f32_e32 v32, v226, v32
	v_add_f32_e32 v29, v223, v29
	v_add_f32_e32 v33, v227, v33
	v_add_f32_e32 v30, v224, v30
	v_add_f32_e32 v31, v225, v31
	v_mul_f32_e32 v28, 0xbfb8aa3b, v28
	v_mul_f32_e32 v32, 0xbfb8aa3b, v32
	v_mul_f32_e32 v29, 0xbfb8aa3b, v29
	v_mul_f32_e32 v33, 0xbfb8aa3b, v33
	v_mul_f32_e32 v30, 0xbfb8aa3b, v30
	v_add_f32_e32 v34, v228, v34
	v_mul_f32_e32 v31, 0xbfb8aa3b, v31
	v_add_f32_e32 v35, v229, v35
	v_exp_f32_e32 v28, v28
	v_exp_f32_e32 v32, v32
	v_exp_f32_e32 v29, v29
	v_exp_f32_e32 v33, v33
	v_exp_f32_e32 v30, v30
	v_mul_f32_e32 v34, 0xbfb8aa3b, v34
	v_exp_f32_e32 v31, v31
	v_mul_f32_e32 v35, 0xbfb8aa3b, v35
	v_exp_f32_e32 v34, v34
	v_exp_f32_e32 v35, v35
	v_add_f32_e32 v28, 1.0, v28
	v_add_f32_e32 v32, 1.0, v32
	v_add_f32_e32 v29, 1.0, v29
	v_add_f32_e32 v33, 1.0, v33
	v_add_f32_e32 v30, 1.0, v30
	v_add_f32_e32 v31, 1.0, v31
	v_rcp_f32_e32 v28, v28
	v_rcp_f32_e32 v32, v32
	v_rcp_f32_e32 v29, v29
	v_rcp_f32_e32 v33, v33
	v_rcp_f32_e32 v30, v30
	v_add_f32_e32 v34, 1.0, v34
	v_rcp_f32_e32 v31, v31
	v_add_f32_e32 v35, 1.0, v35
	v_rcp_f32_e32 v34, v34
	v_rcp_f32_e32 v35, v35
	s_waitcnt vmcnt(9)
	v_lshlrev_b32_e32 v40, 16, v168
	v_and_b32_e32 v36, 0xffff0000, v168
	v_lshlrev_b32_e32 v41, 16, v169
	v_and_b32_e32 v37, 0xffff0000, v169
	v_lshlrev_b32_e32 v42, 16, v170
	v_and_b32_e32 v38, 0xffff0000, v170
	v_lshlrev_b32_e32 v43, 16, v171
	v_and_b32_e32 v39, 0xffff0000, v171
	v_fmac_f32_e32 v40, v24, v28
	v_fmac_f32_e32 v36, v25, v29
	v_fmac_f32_e32 v41, v26, v30
	v_fmac_f32_e32 v37, v27, v31
	v_fmac_f32_e32 v42, v20, v32
	v_fmac_f32_e32 v38, v21, v33
	v_cvt_pk_bf16_f32 v20, v40, v36
	v_cvt_pk_bf16_f32 v21, v41, v37
	v_fmac_f32_e32 v43, v22, v34
	v_fmac_f32_e32 v39, v23, v35
	v_cvt_pk_bf16_f32 v22, v42, v38
	v_cvt_pk_bf16_f32 v23, v43, v39
	global_store_dwordx4 v[88:89], v[20:23], off offset:256
	s_nop 1
	v_lshl_add_u64 v[20:21], v[90:91], 0, v[84:85]
	s_nop 0
	v_lshl_add_u64 v[20:21], s[44:45], 0, v[94:95]
	v_lshl_add_u64 v[20:21], v[20:21], 0, v[84:85]
	s_nop 0
	v_lshl_add_u64 v[20:21], v[96:97], 0, v[84:85]
	s_nop 0
	v_lshl_add_u64 v[20:21], s[44:45], 0, v[98:99]
	v_lshl_add_u64 v[20:21], v[20:21], 0, v[84:85]
	s_nop 0
	s_waitcnt vmcnt(9)
; #define GAS __attribute__((address_space(1)))
; __device__ __forceinline__ void unpack8(const v4u v, float (&f)[8]) { f[0] = bflo(v.x); f[1] = bfhi(v.x); f[2] = bflo(v.y); f[3] = bfhi(v.y); f[4] = bflo(v.z); f[5] = bfhi(v.z); f[6] = bflo(v.w); f[7] = bfhi(v.w); }
; __device__ __forceinline__ v4u pack8(const float (&f)[8]) { v4u o; o.x = cvt_pk_bf16(f[0], f[1]); o.y = cvt_pk_bf16(f[2], f[3]); o.z = cvt_pk_bf16(f[4], f[5]); o.w = cvt_pk_bf16(f[6], f[7]); return o; }
; __device__ __forceinline__ float sigmoidf_(float x) { return __builtin_amdgcn_rcpf(1.f + __expf(-x)); }
;     __device__ __forceinline__ void operator()(const f32x4 (&acc)[2][2][4][2], const pg8::Unit& u, int wr, int wc, int fr, int fq) const {
;     ...
;             for (int aim = 0; aim < 4; ++aim) { const int ai = aim >> 1, mb = (aim & 1) * 2;
;                 v4u gv[4], tv[4];
; #pragma unroll
;                 for (int m = mb; m < mb + 2; ++m) { const int row = row0 + ai * 128 + m * 16;
;                     gv[m] = __builtin_nontemporal_load((const GAS v4u*)(proj + (size_t)row * NPROJ + OFF_GATE + WHICH * DM + col));
;                     if (WHICH == 1) tv[m] = *(const GAS v4u*)(ta + (size_t)row * DM + col); }
; #pragma unroll
;                 for (int m = mb; m < mb + 2; ++m) { const int row = row0 + ai * 128 + m * 16; float g[8]; unpack8(gv[m], g);
;                     const f32x4 a0 = acc[ai][bj][m][0], a1 = acc[ai][bj][m][1]; float r[8];
; #pragma unroll
;                     for (int e = 0; e < 4; ++e) { r[e] = sigmoidf_(g[e] + b0[e]) * a0[e]; r[4 + e] = sigmoidf_(g[4 + e] + b1[e]) * a1[e]; }
;                     if (WHICH == 0) *(GAS v4u*)(ta + (size_t)row * DM + col) = pack8(r);
;                     else { float tf[8]; unpack8(tv[m], tf);
; #pragma unroll
;                         for (int e = 0; e < 8; ++e) r[e] += tf[e];
;                         *(GAS v4u*)(mix + (size_t)row * DM + col) = pack8(r); } }
	v_lshlrev_b32_e32 v36, 16, v108
	v_and_b32_e32 v24, 0xffff0000, v108
	v_lshlrev_b32_e32 v37, 16, v109
	v_and_b32_e32 v25, 0xffff0000, v109
	v_lshlrev_b32_e32 v38, 16, v110
	v_and_b32_e32 v26, 0xffff0000, v110
	v_lshlrev_b32_e32 v39, 16, v111
	v_and_b32_e32 v27, 0xffff0000, v111
	v_add_f32_e32 v36, v222, v36
	v_add_f32_e32 v38, v226, v38
	v_add_f32_e32 v24, v223, v24
	v_add_f32_e32 v26, v227, v26
	v_add_f32_e32 v37, v224, v37
	v_add_f32_e32 v39, v228, v39
	v_add_f32_e32 v25, v225, v25
	v_add_f32_e32 v27, v229, v27
	v_mul_f32_e32 v36, 0xbfb8aa3b, v36
	v_mul_f32_e32 v38, 0xbfb8aa3b, v38
	v_mul_f32_e32 v24, 0xbfb8aa3b, v24
	v_mul_f32_e32 v26, 0xbfb8aa3b, v26
	v_mul_f32_e32 v37, 0xbfb8aa3b, v37
	v_mul_f32_e32 v39, 0xbfb8aa3b, v39
	v_mul_f32_e32 v25, 0xbfb8aa3b, v25
	v_mul_f32_e32 v27, 0xbfb8aa3b, v27
	v_exp_f32_e32 v36, v36
	v_exp_f32_e32 v38, v38
	v_exp_f32_e32 v24, v24
	v_exp_f32_e32 v26, v26
	v_exp_f32_e32 v37, v37
	v_exp_f32_e32 v39, v39
	v_exp_f32_e32 v25, v25
	v_exp_f32_e32 v27, v27
	v_add_f32_e32 v36, 1.0, v36
	v_add_f32_e32 v38, 1.0, v38
	v_add_f32_e32 v24, 1.0, v24
	v_add_f32_e32 v26, 1.0, v26
	v_add_f32_e32 v37, 1.0, v37
	v_add_f32_e32 v39, 1.0, v39
	v_add_f32_e32 v25, 1.0, v25
	v_add_f32_e32 v27, 1.0, v27
	v_rcp_f32_e32 v36, v36
	v_rcp_f32_e32 v38, v38
	v_rcp_f32_e32 v24, v24
	v_rcp_f32_e32 v26, v26
	v_rcp_f32_e32 v37, v37
	v_rcp_f32_e32 v39, v39
	v_rcp_f32_e32 v25, v25
	v_rcp_f32_e32 v27, v27
	s_waitcnt vmcnt(8)
	v_lshlrev_b32_e32 v40, 16, v68
	v_and_b32_e32 v28, 0xffff0000, v68
	v_lshlrev_b32_e32 v41, 16, v69
	v_and_b32_e32 v29, 0xffff0000, v69
	v_lshlrev_b32_e32 v42, 16, v70
	v_and_b32_e32 v30, 0xffff0000, v70
	v_lshlrev_b32_e32 v43, 16, v71
	v_and_b32_e32 v31, 0xffff0000, v71
	v_fmac_f32_e32 v40, v16, v36
	v_fmac_f32_e32 v28, v17, v24
	v_fmac_f32_e32 v41, v18, v37
	v_fmac_f32_e32 v29, v19, v25
	v_fmac_f32_e32 v42, v12, v38
	v_fmac_f32_e32 v30, v13, v26
	v_fmac_f32_e32 v43, v14, v39
	v_fmac_f32_e32 v31, v15, v27
	v_cvt_pk_bf16_f32 v12, v40, v28
	v_cvt_pk_bf16_f32 v13, v41, v29
	v_cvt_pk_bf16_f32 v14, v42, v30
	v_cvt_pk_bf16_f32 v15, v43, v31
	global_store_dwordx4 v[82:83], v[12:15], off offset:256
	s_waitcnt vmcnt(7)
	v_lshlrev_b32_e32 v16, 16, v220
	v_and_b32_e32 v17, 0xffff0000, v220
	v_lshlrev_b32_e32 v12, 16, v218
	v_and_b32_e32 v13, 0xffff0000, v218
	v_lshlrev_b32_e32 v14, 16, v219
	v_and_b32_e32 v15, 0xffff0000, v219
	v_lshlrev_b32_e32 v18, 16, v221
	v_and_b32_e32 v19, 0xffff0000, v221
	v_add_f32_e32 v12, v222, v12
	v_add_f32_e32 v16, v226, v16
	v_add_f32_e32 v13, v223, v13
	v_add_f32_e32 v17, v227, v17
	v_add_f32_e32 v14, v224, v14
	v_add_f32_e32 v18, v228, v18
	v_add_f32_e32 v15, v225, v15
	v_add_f32_e32 v19, v229, v19
	v_mul_f32_e32 v12, 0xbfb8aa3b, v12
	v_mul_f32_e32 v16, 0xbfb8aa3b, v16
	v_mul_f32_e32 v13, 0xbfb8aa3b, v13
	v_mul_f32_e32 v17, 0xbfb8aa3b, v17
	v_mul_f32_e32 v14, 0xbfb8aa3b, v14
	v_mul_f32_e32 v18, 0xbfb8aa3b, v18
	v_mul_f32_e32 v15, 0xbfb8aa3b, v15
	v_mul_f32_e32 v19, 0xbfb8aa3b, v19
	v_exp_f32_e32 v12, v12
	v_exp_f32_e32 v16, v16
	v_exp_f32_e32 v13, v13
	v_exp_f32_e32 v17, v17
	v_exp_f32_e32 v14, v14
	v_exp_f32_e32 v18, v18
	v_exp_f32_e32 v15, v15
	v_exp_f32_e32 v19, v19
	v_add_f32_e32 v12, 1.0, v12
	v_add_f32_e32 v16, 1.0, v16
	v_add_f32_e32 v13, 1.0, v13
	v_add_f32_e32 v17, 1.0, v17
	v_add_f32_e32 v14, 1.0, v14
	v_add_f32_e32 v18, 1.0, v18
	v_add_f32_e32 v15, 1.0, v15
	v_add_f32_e32 v19, 1.0, v19
	v_rcp_f32_e32 v12, v12
	v_rcp_f32_e32 v16, v16
	v_rcp_f32_e32 v13, v13
	v_rcp_f32_e32 v17, v17
	v_rcp_f32_e32 v14, v14
	v_rcp_f32_e32 v18, v18
	v_rcp_f32_e32 v15, v15
	v_rcp_f32_e32 v19, v19
	s_waitcnt vmcnt(6)
	v_lshlrev_b32_e32 v24, 16, v196
	v_and_b32_e32 v20, 0xffff0000, v196
	v_lshlrev_b32_e32 v25, 16, v197
	v_and_b32_e32 v21, 0xffff0000, v197
	v_lshlrev_b32_e32 v26, 16, v198
	v_and_b32_e32 v22, 0xffff0000, v198
	v_lshlrev_b32_e32 v27, 16, v199
	v_and_b32_e32 v23, 0xffff0000, v199
	v_fmac_f32_e32 v24, v8, v12
	v_fmac_f32_e32 v20, v9, v13
	v_fmac_f32_e32 v25, v10, v14
	v_fmac_f32_e32 v21, v11, v15
	v_fmac_f32_e32 v26, v4, v16
	v_fmac_f32_e32 v22, v5, v17
	v_fmac_f32_e32 v27, v6, v18
	v_fmac_f32_e32 v23, v7, v19
	v_cvt_pk_bf16_f32 v4, v24, v20
	v_cvt_pk_bf16_f32 v5, v25, v21
	v_cvt_pk_bf16_f32 v6, v26, v22
	v_cvt_pk_bf16_f32 v7, v27, v23
	global_store_dwordx4 v[80:81], v[4:7], off offset:256
	s_cbranch_vccnz .LBB0_477
	s_andn2_b64 vcc, exec, s[36:37]
	s_cbranch_vccnz .LBB0_476
	s_barrier
	s_branch .LBB0_476
